# GLA gate columns in G1 and G3: wave-uniform bias/weight values fetched by scalar loads one column ahead instead of serialized per-lane vector loads
# speedup vs baseline: 1.0221x; 1.0221x over previous
; __device__ __forceinline__ u32x4 pack8(const f32x4 v0, const f32x4 v1) { u32x4 w; w.x = cvt_pk_bf16(v0[0], v0[1]); w.y = cvt_pk_bf16(v0[2], v0[3]); w.z = cvt_pk_bf16(v1[0], v1[1]); w.w = cvt_pk_bf16(v1[2], v1[3]); return w; }
; #define LAS __attribute__((address_space(3)))
; __device__ __forceinline__ void gla_g3_phase(LAS unsigned char* lds, const bf16_t* PROJ, const bf16_t* ALOW, const float* wa2, const float* ba, const float* gn, const bf16_t* UPD, bf16_t* MIXIN, int G, int tid) {
;     LAS bf16_t* KE = (LAS bf16_t*)lds; LAS bf16_t* QE = (LAS bf16_t*)(lds + 9216); LAS bf16_t* VT = (LAS bf16_t*)(lds + 18432); LAS float* RED = (LAS float*)(lds + 36864);
;     const int lane = tid & 63, wave = __builtin_amdgcn_readfirstlane(tid >> 6);
;     const int eb = wave >> 1, cb = wave & 1, i = lane & 31, kg = lane >> 5;
;     G3In cur; if ((int)blockIdx.x < 2048) cur = g3_load(PROJ, ALOW, UPD, blockIdx.x, lane, wave);
;     for (int u = blockIdx.x; u < 2048; u += G) {
;         G3In nxt; if (u + G < 2048) nxt = g3_load(PROJ, ALOW, UPD, u + G, lane, wave);
;         const int bh = u >> 7, n = u & 127, b = bh >> 2, h = bh & 3, row0 = b * SEQ + n * 64;
;         const size_t row = (size_t)(row0 + 32 * cb + i);
;         { float bc[8], bl[8];
;           gla_bcum(cur.a0, cur.a1, wa2, ba, h, lane, wave, bc, bl);
;           float qf[8], kf[8]; unpack8(cur.q, qf); unpack8(cur.k, kf);
;           f32x4 q0, q1, k0, k1;
; #pragma unroll
;           for (int x = 0; x < 4; ++x) { q0[x] = qf[x] * 0.125f * __expf(bc[x]); q1[x] = qf[4 + x] * 0.125f * __expf(bc[4 + x]); k0[x] = kf[x] * __expf(-bc[x]); k1[x] = kf[4 + x] * __expf(-bc[4 + x]); }
;           *(LAS u32x4*)(QE + lane * GP + 8 * wave) = pg8::pack8(q0, q1); *(LAS u32x4*)(KE + lane * GP + 8 * wave) = pg8::pack8(k0, k1);
;           const int pcol = slot32(lane);
; #pragma unroll
;           for (int pc = 0; pc < 2; ++pc) { const int e0 = 64 * pc + 8 * wave; const u32x4 v = pc ? cur.v1 : cur.v0;
; #pragma unroll
;               for (int x = 0; x < 4; ++x) { VT[(e0 + 2 * x) * GP + pcol] = (bf16_t)(v[x] & 0xffffu); VT[(e0 + 2 * x + 1) * GP + pcol] = (bf16_t)(v[x] >> 16); } } }
;         GLA_BAR();
;         bf16x8_t qb[4];
; #pragma unroll
;         for (int s = 0; s < 4; ++s) qb[s] = *(const LAS bf16x8_t*)(QE + (32 * cb + i) * GP + 16 * s + 8 * kg);
.LBB0_342:
	s_and_b64 vcc, exec, s[8:9]
	s_cbranch_vccnz .LBB0_418
	s_load_dwordx2 s[4:5], s[4:5], 0x0
	s_nop 0
	s_load_dwordx2 s[8:9], s[10:11], 0x0
	s_nop 0
	s_load_dwordx2 s[10:11], s[12:13], 0x0
	v_readlane_b32 s12, v253, 47
	v_readlane_b32 s13, v253, 48
	s_lshl_b64 s[12:13], s[12:13], 2
	s_waitcnt lgkmcnt(0)
	s_add_u32 s4, s4, s12
	v_writelane_b32 v255, s4, 17
	s_addc_u32 s4, s5, s13
	v_writelane_b32 v255, s4, 18
	v_readlane_b32 s4, v253, 49
	v_readlane_b32 s5, v253, 50
	s_lshl_b64 s[4:5], s[4:5], 2
	s_add_u32 s4, s8, s4
	v_writelane_b32 v255, s4, 19
	s_addc_u32 s4, s9, s5
	v_writelane_b32 v255, s4, 20
	v_lshlrev_b32_e32 v28, 2, v27
	v_readlane_b32 s4, v255, 8
	v_readlane_b32 s5, v255, 9
	s_add_u32 s4, s10, s4
	s_addc_u32 s5, s11, s5
	s_lshl_b32 s15, s6, 4
	s_ashr_i32 s7, s7, 7
	s_and_b32 s48, s15, 0xffffffe0
	v_mul_u32_u24_e32 v27, 0x48, v172
	s_add_i32 s15, s15, 0
	v_lshl_add_u32 v127, v27, 1, s15
	s_lshl_b32 s15, s7, 5
	v_lshlrev_b32_e32 v27, 1, v172
	v_lshrrev_b32_e32 v30, 1, v170
	v_or_b32_e32 v104, s15, v28
	s_and_b32 s14, s6, 1
	s_lshl_b32 s78, s6, 3
	s_lshl_b32 s8, s6, 5
	v_and_b32_e32 v27, 8, v27
	v_and_b32_e32 v29, 51, v170
	v_and_b32_e32 v30, 4, v30
	v_ashrrev_i32_e32 v105, 31, v104
	s_mulk_i32 s6, 0x480
	v_or3_b32 v27, v30, v29, v27
	v_lshl_add_u64 v[106:107], v[104:105], 2, s[4:5]
	s_add_i32 s4, s6, 0
	v_lshl_add_u32 v131, v27, 1, s4
	v_or_b32_e32 v27, 2, v28
	v_cmp_gt_u32_e64 s[18:19], v27, v26
	v_or_b32_e32 v27, 3, v28
	v_cmp_gt_u32_e64 s[20:21], v27, v26
	v_or_b32_e32 v27, 8, v28
	v_lshl_or_b32 v128, s14, 5, v26
	s_movk_i32 s16, 0x90
	v_or_b32_e32 v31, s15, v26
	s_lshl_b32 s7, s7, 8
	v_cmp_gt_u32_e64 s[22:23], v27, v26
	v_or_b32_e32 v27, 9, v28
	v_mad_u32_u24 v29, v128, s16, 0
	v_mul_lo_u32 v31, v31, s16
	s_add_i32 s7, s7, 0
	s_lshl_b32 s16, s14, 7
	v_cmp_gt_u32_e64 s[24:25], v27, v26
	v_or_b32_e32 v27, 10, v28
	s_ashr_i32 s79, s78, 31
	s_ashr_i32 s49, s48, 31
	s_add_i32 s7, s7, s16
	s_add_i32 s16, s16, 0
	v_cmp_gt_u32_e64 s[26:27], v27, v26
	v_or_b32_e32 v27, 11, v28
	s_cmp_eq_u32 s14, 0
	v_cmp_gt_u32_e64 s[28:29], v27, v26
	v_or_b32_e32 v27, 16, v28
	s_cselect_b64 s[4:5], -1, 0
	v_cmp_gt_u32_e64 s[30:31], v27, v26
	v_or_b32_e32 v27, 17, v28
	v_writelane_b32 v255, s4, 21
	s_cmp_eq_u32 s14, 1
	v_cmp_gt_u32_e64 s[34:35], v27, v26
	v_or_b32_e32 v27, 18, v28
	v_writelane_b32 v255, s5, 22
	s_cselect_b64 s[4:5], -1, 0
	v_cmp_gt_u32_e64 s[36:37], v27, v26
	v_or_b32_e32 v27, 19, v28
	v_writelane_b32 v255, s4, 23
	v_cmp_gt_u32_e64 s[38:39], v27, v26
	v_or_b32_e32 v27, 24, v28
	v_writelane_b32 v255, s5, 24
	v_cmp_gt_u32_e64 s[4:5], v28, v26
	v_cmp_gt_u32_e64 s[40:41], v27, v26
	v_or_b32_e32 v27, 25, v28
	v_writelane_b32 v255, s4, 25
	v_cmp_gt_u32_e64 s[42:43], v27, v26
	v_or_b32_e32 v27, 26, v28
	v_lshlrev_b32_e32 v25, 2, v26
	v_writelane_b32 v255, s5, 26
	v_cmp_gt_u32_e64 s[44:45], v27, v26
	v_or_b32_e32 v27, 27, v28
	v_and_or_b32 v126, s8, 32, v26
	v_add_u32_e32 v129, s7, v25
	v_add_u32_e32 v130, s16, v25
	v_mul_u32_u24_e32 v25, 0x90, v26
	v_cmp_lt_u32_e64 s[16:17], v28, v26
	v_cmp_gt_u32_e64 s[46:47], v27, v26
	v_or_b32_e32 v26, s48, v26
	v_writelane_b32 v255, s48, 27
	v_and_b32_e32 v32, 32, v170
	v_lshrrev_b32_e32 v32, 1, v32
	v_mov_b32_e32 v27, s49
	v_lshlrev_b64 v[26:27], 7, v[26:27]
	v_readlane_b32 s4, v253, 15
	v_add_u32_e32 v30, 0, v24
	v_add_u32_e32 v31, 0, v31
	v_or_b32_e32 v26, v26, v32
	v_readlane_b32 s5, v253, 16
	v_cmp_gt_u32_e64 s[8:9], 48, v172
	v_cmp_gt_u32_e64 s[10:11], 32, v172
	v_cmp_lt_u32_e64 s[12:13], 15, v172
	v_writelane_b32 v255, s49, 28
	v_lshl_add_u64 v[108:109], s[4:5], 0, v[26:27]
	v_lshlrev_b32_e32 v164, 1, v28
	v_add_u32_e32 v132, v29, v24
	v_add_u32_e32 v133, v30, v25
	v_add_u32_e32 v134, v31, v24
	v_readlane_b32 s64, v250, 51
	v_readlane_b32 s65, v250, 52
	s_mov_b32 s6, s2
	s_waitcnt vmcnt(0)
	s_branch .LBB0_345

; __device__ __forceinline__ void gla_bcum(const u32x4 a0, const u32x4 a1, const float* wa2, const float* ba, int h, int lane, int wave, float (&bc)[8], float (&bl)[8]) {
;     float al[16];
; #pragma unroll
;     for (int x = 0; x < 4; ++x) { al[2 * x] = __uint_as_float(a0[x] << 16); al[2 * x + 1] = __uint_as_float(a0[x] & 0xffff0000u); al[8 + 2 * x] = __uint_as_float(a1[x] << 16); al[8 + 2 * x + 1] = __uint_as_float(a1[x] & 0xffff0000u); }
; #pragma unroll
;     for (int x = 0; x < 8; ++x) { const int col = h * 64 + 8 * wave + x; float z = ba[col];
; #pragma unroll
;         for (int i = 0; i < 16; ++i) z += al[i] * wa2[i * 256 + col];
;         float la = (fminf(z, 0.f) - __logf(1.f + __expf(-fabsf(z)))) * (1.f / 16.f);
;         la += __builtin_bit_cast(float, __builtin_amdgcn_update_dpp(0, __builtin_bit_cast(int, la), 0x111, 0xf, 0xf, true));
;         la += __builtin_bit_cast(float, __builtin_amdgcn_update_dpp(0, __builtin_bit_cast(int, la), 0x112, 0xf, 0xf, true));
;         la += __builtin_bit_cast(float, __builtin_amdgcn_update_dpp(0, __builtin_bit_cast(int, la), 0x114, 0xf, 0xf, true));
;         la += __builtin_bit_cast(float, __builtin_amdgcn_update_dpp(0, __builtin_bit_cast(int, la), 0x118, 0xf, 0xf, true));
;         const float t0 = __builtin_bit_cast(float, __builtin_amdgcn_readlane(__builtin_bit_cast(int, la), 15)), t1 = __builtin_bit_cast(float, __builtin_amdgcn_readlane(__builtin_bit_cast(int, la), 31)),
;                     t2 = __builtin_bit_cast(float, __builtin_amdgcn_readlane(__builtin_bit_cast(int, la), 47)), t3 = __builtin_bit_cast(float, __builtin_amdgcn_readlane(__builtin_bit_cast(int, la), 63));
;         la += (lane >= 48) ? (t0 + t1) + t2 : (lane >= 32) ? t0 + t1 : (lane >= 16) ? t0 : 0.f;
;         bc[x] = la; bl[x] = ((t0 + t1) + t2) + t3; }
.LBB0_347:
	s_bfe_u32 s74, s6, 0x20007
	s_lshl_b32 s4, s74, 6
	s_add_i32 s6, s4, s78
	s_ashr_i32 s7, s6, 31
	s_lshl_b64 s[6:7], s[6:7], 2
	v_readlane_b32 s4, v255, 19
	s_add_u32 s76, s4, s6
	v_readlane_b32 s4, v255, 20
	s_addc_u32 s77, s4, s7
	v_readlane_b32 s4, v255, 17
	s_add_u32 s48, s4, s6
	v_readlane_b32 s4, v255, 18
	s_addc_u32 s49, s4, s7
	v_writelane_b32 v255, s82, 29
	v_writelane_b32 v255, s83, 30
	v_writelane_b32 v255, s84, 31
	v_writelane_b32 v255, s85, 32
	v_writelane_b32 v255, s86, 33
	v_writelane_b32 v255, s87, 34
	v_writelane_b32 v255, s88, 35
	v_writelane_b32 v255, s89, 36
	v_writelane_b32 v255, s90, 37
	v_writelane_b32 v255, s91, 38
	v_writelane_b32 v255, s94, 39
	v_writelane_b32 v255, s95, 40
	v_writelane_b32 v255, s96, 41
	v_writelane_b32 v255, s97, 42
	v_writelane_b32 v255, s51, 43
	v_writelane_b32 v255, s52, 44
	v_writelane_b32 v255, s53, 45
	s_load_dword s82, s[76:77], 0x0
	s_load_dword s83, s[48:49], 0x0
	s_load_dword s84, s[48:49], 0x400
	s_load_dword s85, s[48:49], 0x800
	s_load_dword s86, s[48:49], 0xc00
	s_load_dword s87, s[48:49], 0x1000
	s_load_dword s88, s[48:49], 0x1400
	s_load_dword s89, s[48:49], 0x1800
	s_load_dword s90, s[48:49], 0x1c00
	s_load_dword s91, s[48:49], 0x2000
	s_load_dword s94, s[48:49], 0x2400
	s_load_dword s95, s[48:49], 0x2800
	s_load_dword s96, s[48:49], 0x2c00
	s_load_dword s97, s[48:49], 0x3000
	s_load_dword s51, s[48:49], 0x3400
	s_load_dword s52, s[48:49], 0x3800
	s_load_dword s53, s[48:49], 0x3c00
	v_lshlrev_b32_e32 v92, 16, v16
	v_and_b32_e32 v91, 0xffff0000, v16
	v_lshlrev_b32_e32 v90, 16, v17
	v_and_b32_e32 v89, 0xffff0000, v17
	v_lshlrev_b32_e32 v88, 16, v18
	v_and_b32_e32 v31, 0xffff0000, v18
	v_lshlrev_b32_e32 v30, 16, v19
	v_and_b32_e32 v29, 0xffff0000, v19
	v_lshlrev_b32_e32 v28, 16, v20
	v_and_b32_e32 v27, 0xffff0000, v20
	v_lshlrev_b32_e32 v26, 16, v21
	v_and_b32_e32 v25, 0xffff0000, v21
	v_lshlrev_b32_e32 v24, 16, v22
	v_and_b32_e32 v20, 0xffff0000, v22
	v_lshlrev_b32_e32 v19, 16, v23
	v_and_b32_e32 v18, 0xffff0000, v23
	s_mov_b32 s4, 0xbfb8aa3b
	s_waitcnt lgkmcnt(0)
	v_mov_b32_e32 v93, s82
	v_fmac_f32_e32 v93, s83, v92
	v_fmac_f32_e32 v93, s84, v91
	v_fmac_f32_e32 v93, s85, v90
	v_fmac_f32_e32 v93, s86, v89
	v_fmac_f32_e32 v93, s87, v88
	v_fmac_f32_e32 v93, s88, v31
	v_fmac_f32_e32 v93, s89, v30
	v_fmac_f32_e32 v93, s90, v29
	v_fmac_f32_e32 v93, s91, v28
	v_fmac_f32_e32 v93, s94, v27
	v_fmac_f32_e32 v93, s95, v26
	v_fmac_f32_e32 v93, s96, v25
	v_fmac_f32_e32 v93, s97, v24
	v_fmac_f32_e32 v93, s51, v20
	v_fmac_f32_e32 v93, s52, v19
	v_fmac_f32_e32 v93, s53, v18
	s_load_dword s82, s[76:77], 0x4
	s_load_dword s83, s[48:49], 0x4
	s_load_dword s84, s[48:49], 0x404
	s_load_dword s85, s[48:49], 0x804
	s_load_dword s86, s[48:49], 0xc04
	s_load_dword s87, s[48:49], 0x1004
	s_load_dword s88, s[48:49], 0x1404
	s_load_dword s89, s[48:49], 0x1804
	s_load_dword s90, s[48:49], 0x1c04
	s_load_dword s91, s[48:49], 0x2004
	s_load_dword s94, s[48:49], 0x2404
	s_load_dword s95, s[48:49], 0x2804
	s_load_dword s96, s[48:49], 0x2c04
	s_load_dword s97, s[48:49], 0x3004
	s_load_dword s51, s[48:49], 0x3404
	s_load_dword s52, s[48:49], 0x3804
	s_load_dword s53, s[48:49], 0x3c04
	v_mul_f32_e64 v16, |v93|, s4
	v_exp_f32_e32 v16, v16
	s_mov_b32 s4, 0x3f317217
	v_add_f32_e32 v16, 1.0, v16
	v_cmp_gt_f32_e32 vcc, s81, v16
	s_nop 1
	v_cndmask_b32_e64 v17, 0, 32, vcc
	v_ldexp_f32 v16, v16, v17
	v_log_f32_e32 v16, v16
	v_cndmask_b32_e32 v21, 0, v231, vcc
	v_min_f32_e32 v17, 0, v93
	v_mul_f32_e32 v22, 0x3f317217, v16
	v_fma_f32 v22, v16, s4, -v22
	v_fmac_f32_e32 v22, 0x3377d1cf, v16
	s_mov_b32 s4, 0x7f800000
	v_fmac_f32_e32 v22, 0x3f317217, v16
	v_cmp_lt_f32_e64 vcc, |v16|, s4
	s_nop 1
	v_cndmask_b32_e32 v16, v16, v22, vcc
	v_sub_f32_e32 v16, v16, v21
	v_sub_f32_e32 v16, v17, v16
	v_mul_f32_e32 v17, 0x3d800000, v16
	s_nop 1
	v_mov_b32_dpp v17, v17 row_shr:1 row_mask:0xf bank_mask:0xf bound_ctrl:1
	v_fmac_f32_e32 v17, 0x3d800000, v16
	s_nop 1
	v_add_f32_dpp v16, v17, v17 row_shr:2 row_mask:0xf bank_mask:0xf bound_ctrl:1
	s_nop 1
	v_add_f32_dpp v16, v16, v16 row_shr:4 row_mask:0xf bank_mask:0xf bound_ctrl:1
	s_nop 1
	v_add_f32_dpp v16, v16, v16 row_shr:8 row_mask:0xf bank_mask:0xf bound_ctrl:1
	s_nop 0
	v_readlane_b32 s71, v16, 15
	v_readlane_b32 s59, v16, 31
	v_readlane_b32 s58, v16, 47
	s_and_saveexec_b64 s[6:7], s[8:9]
	s_xor_b64 vcc, exec, s[6:7]
	s_cbranch_execz .LBB0_353
	s_and_saveexec_b64 s[4:5], s[10:11]
	s_xor_b64 s[6:7], exec, s[4:5]
	v_mov_b32_e32 v17, s71
	v_cndmask_b32_e64 v17, 0, v17, s[12:13]
	s_andn2_saveexec_b64 s[6:7], s[6:7]
	v_mov_b32_e32 v17, s59
	v_add_f32_e32 v17, s71, v17
	s_or_b64 exec, exec, s[6:7]
; __device__ __forceinline__ void gla_bcum(const u32x4 a0, const u32x4 a1, const float* wa2, const float* ba, int h, int lane, int wave, float (&bc)[8], float (&bl)[8]) {
;     ...
;     for (int x = 0; x < 4; ++x) { al[2 * x] = __uint_as_float(a0[x] << 16); al[2 * x + 1] = __uint_as_float(a0[x] & 0xffff0000u); al[8 + 2 * x] = __uint_as_float(a1[x] << 16); al[8 + 2 * x + 1] = __uint_as_float(a1[x] & 0xffff0000u); }
; #pragma unroll
;     for (int x = 0; x < 8; ++x) { const int col = h * 64 + 8 * wave + x; float z = ba[col];
; #pragma unroll
;         for (int i = 0; i < 16; ++i) z += al[i] * wa2[i * 256 + col];
;         float la = (fminf(z, 0.f) - __logf(1.f + __expf(-fabsf(z)))) * (1.f / 16.f);
;         la += __builtin_bit_cast(float, __builtin_amdgcn_update_dpp(0, __builtin_bit_cast(int, la), 0x111, 0xf, 0xf, true));
;         la += __builtin_bit_cast(float, __builtin_amdgcn_update_dpp(0, __builtin_bit_cast(int, la), 0x112, 0xf, 0xf, true));
;         la += __builtin_bit_cast(float, __builtin_amdgcn_update_dpp(0, __builtin_bit_cast(int, la), 0x114, 0xf, 0xf, true));
;         la += __builtin_bit_cast(float, __builtin_amdgcn_update_dpp(0, __builtin_bit_cast(int, la), 0x118, 0xf, 0xf, true));
;         const float t0 = __builtin_bit_cast(float, __builtin_amdgcn_readlane(__builtin_bit_cast(int, la), 15)), t1 = __builtin_bit_cast(float, __builtin_amdgcn_readlane(__builtin_bit_cast(int, la), 31)),
;                     t2 = __builtin_bit_cast(float, __builtin_amdgcn_readlane(__builtin_bit_cast(int, la), 47)), t3 = __builtin_bit_cast(float, __builtin_amdgcn_readlane(__builtin_bit_cast(int, la), 63));
;         la += (lane >= 48) ? (t0 + t1) + t2 : (lane >= 32) ? t0 + t1 : (lane >= 16) ? t0 : 0.f;
;         bc[x] = la; bl[x] = ((t0 + t1) + t2) + t3; }
.LBB0_353:
	s_andn2_saveexec_b64 vcc, vcc
	v_mov_b32_e32 v17, s59
	v_add_f32_e32 v17, s71, v17
	v_add_f32_e32 v17, s58, v17
	s_or_b64 exec, exec, vcc
	s_mov_b32 s4, 0xbfb8aa3b
	s_waitcnt lgkmcnt(0)
	v_mov_b32_e32 v21, s82
	v_fmac_f32_e32 v21, s83, v92
	v_fmac_f32_e32 v21, s84, v91
	v_fmac_f32_e32 v21, s85, v90
	v_fmac_f32_e32 v21, s86, v89
	v_fmac_f32_e32 v21, s87, v88
	v_fmac_f32_e32 v21, s88, v31
	v_fmac_f32_e32 v21, s89, v30
	v_fmac_f32_e32 v21, s90, v29
	v_fmac_f32_e32 v21, s91, v28
	v_fmac_f32_e32 v21, s94, v27
	v_fmac_f32_e32 v21, s95, v26
	v_fmac_f32_e32 v21, s96, v25
	v_fmac_f32_e32 v21, s97, v24
	v_fmac_f32_e32 v21, s51, v20
	v_fmac_f32_e32 v21, s52, v19
	v_fmac_f32_e32 v21, s53, v18
	s_load_dword s82, s[76:77], 0x8
	s_load_dword s83, s[48:49], 0x8
	s_load_dword s84, s[48:49], 0x408
	s_load_dword s85, s[48:49], 0x808
	s_load_dword s86, s[48:49], 0xc08
	s_load_dword s87, s[48:49], 0x1008
	s_load_dword s88, s[48:49], 0x1408
	s_load_dword s89, s[48:49], 0x1808
	s_load_dword s90, s[48:49], 0x1c08
	s_load_dword s91, s[48:49], 0x2008
	s_load_dword s94, s[48:49], 0x2408
	s_load_dword s95, s[48:49], 0x2808
	s_load_dword s96, s[48:49], 0x2c08
	s_load_dword s97, s[48:49], 0x3008
	s_load_dword s51, s[48:49], 0x3408
	s_load_dword s52, s[48:49], 0x3808
	s_load_dword s53, s[48:49], 0x3c08
	v_mul_f32_e64 v22, |v21|, s4
	v_exp_f32_e32 v22, v22
	s_mov_b32 s4, 0x3f317217
	v_min_f32_e32 v21, 0, v21
	v_add_f32_e32 v22, 1.0, v22
	v_cmp_gt_f32_e32 vcc, s81, v22
	s_nop 1
	v_cndmask_b32_e64 v23, 0, 32, vcc
	v_ldexp_f32 v22, v22, v23
	v_log_f32_e32 v22, v22
	v_cndmask_b32_e32 v23, 0, v231, vcc
	v_mul_f32_e32 v93, 0x3f317217, v22
	v_fma_f32 v93, v22, s4, -v93
	v_fmac_f32_e32 v93, 0x3377d1cf, v22
	s_mov_b32 s4, 0x7f800000
	v_fmac_f32_e32 v93, 0x3f317217, v22
	v_cmp_lt_f32_e64 vcc, |v22|, s4
	s_nop 1
	v_cndmask_b32_e32 v22, v22, v93, vcc
	v_sub_f32_e32 v22, v22, v23
	v_sub_f32_e32 v21, v21, v22
	v_mul_f32_e32 v22, 0x3d800000, v21
	s_nop 1
	v_mov_b32_dpp v22, v22 row_shr:1 row_mask:0xf bank_mask:0xf bound_ctrl:1
	v_fmac_f32_e32 v22, 0x3d800000, v21
	s_nop 1
	v_add_f32_dpp v21, v22, v22 row_shr:2 row_mask:0xf bank_mask:0xf bound_ctrl:1
	s_nop 1
	v_add_f32_dpp v21, v21, v21 row_shr:4 row_mask:0xf bank_mask:0xf bound_ctrl:1
	s_nop 1
	v_add_f32_dpp v21, v21, v21 row_shr:8 row_mask:0xf bank_mask:0xf bound_ctrl:1
	s_nop 0
	v_readlane_b32 s58, v21, 15
	v_readlane_b32 s71, v21, 31
	v_readlane_b32 s59, v21, 47
	s_and_saveexec_b64 s[4:5], s[8:9]
	s_xor_b64 vcc, exec, s[4:5]
	s_cbranch_execz .LBB0_361
	s_and_saveexec_b64 s[4:5], s[10:11]
	s_xor_b64 s[6:7], exec, s[4:5]
	v_mov_b32_e32 v22, s58
	v_cndmask_b32_e64 v22, 0, v22, s[12:13]
	s_andn2_saveexec_b64 s[6:7], s[6:7]
	v_mov_b32_e32 v22, s71
	v_add_f32_e32 v22, s58, v22
	s_or_b64 exec, exec, s[6:7]
.LBB0_361:
	s_andn2_saveexec_b64 vcc, vcc
	v_mov_b32_e32 v22, s71
	v_add_f32_e32 v22, s58, v22
	v_add_f32_e32 v22, s59, v22
	s_or_b64 exec, exec, vcc
	s_mov_b32 s4, 0xbfb8aa3b
	s_waitcnt lgkmcnt(0)
	v_mov_b32_e32 v23, s82
	v_fmac_f32_e32 v23, s83, v92
	v_fmac_f32_e32 v23, s84, v91
	v_fmac_f32_e32 v23, s85, v90
	v_fmac_f32_e32 v23, s86, v89
	v_fmac_f32_e32 v23, s87, v88
	v_fmac_f32_e32 v23, s88, v31
	v_fmac_f32_e32 v23, s89, v30
	v_fmac_f32_e32 v23, s90, v29
	v_fmac_f32_e32 v23, s91, v28
	v_fmac_f32_e32 v23, s94, v27
	v_fmac_f32_e32 v23, s95, v26
	v_fmac_f32_e32 v23, s96, v25
	v_fmac_f32_e32 v23, s97, v24
	v_fmac_f32_e32 v23, s51, v20
	v_fmac_f32_e32 v23, s52, v19
	v_fmac_f32_e32 v23, s53, v18
	s_load_dword s82, s[76:77], 0xc
	s_load_dword s83, s[48:49], 0xc
	s_load_dword s84, s[48:49], 0x40c
	s_load_dword s85, s[48:49], 0x80c
	s_load_dword s86, s[48:49], 0xc0c
	s_load_dword s87, s[48:49], 0x100c
	s_load_dword s88, s[48:49], 0x140c
	s_load_dword s89, s[48:49], 0x180c
	s_load_dword s90, s[48:49], 0x1c0c
	s_load_dword s91, s[48:49], 0x200c
	s_load_dword s94, s[48:49], 0x240c
	s_load_dword s95, s[48:49], 0x280c
	s_load_dword s96, s[48:49], 0x2c0c
	s_load_dword s97, s[48:49], 0x300c
	s_load_dword s51, s[48:49], 0x340c
	s_load_dword s52, s[48:49], 0x380c
	s_load_dword s53, s[48:49], 0x3c0c
	v_mul_f32_e64 v93, |v23|, s4
	v_exp_f32_e32 v93, v93
	s_mov_b32 s4, 0x3f317217
	v_min_f32_e32 v23, 0, v23
	v_add_f32_e32 v93, 1.0, v93
	v_cmp_gt_f32_e32 vcc, s81, v93
	s_nop 1
	v_cndmask_b32_e64 v94, 0, 32, vcc
	v_ldexp_f32 v93, v93, v94
	v_log_f32_e32 v93, v93
	v_cndmask_b32_e32 v94, 0, v231, vcc
	v_mul_f32_e32 v95, 0x3f317217, v93
	v_fma_f32 v95, v93, s4, -v95
	v_fmac_f32_e32 v95, 0x3377d1cf, v93
	s_mov_b32 s4, 0x7f800000
	v_fmac_f32_e32 v95, 0x3f317217, v93
	v_cmp_lt_f32_e64 vcc, |v93|, s4
	s_nop 1
	v_cndmask_b32_e32 v93, v93, v95, vcc
	v_sub_f32_e32 v93, v93, v94
	v_sub_f32_e32 v23, v23, v93
	v_mul_f32_e32 v93, 0x3d800000, v23
	s_nop 1
	v_mov_b32_dpp v93, v93 row_shr:1 row_mask:0xf bank_mask:0xf bound_ctrl:1
	v_fmac_f32_e32 v93, 0x3d800000, v23
	s_nop 1
	v_add_f32_dpp v23, v93, v93 row_shr:2 row_mask:0xf bank_mask:0xf bound_ctrl:1
	s_nop 1
	v_add_f32_dpp v23, v23, v23 row_shr:4 row_mask:0xf bank_mask:0xf bound_ctrl:1
	s_nop 1
	v_add_f32_dpp v23, v23, v23 row_shr:8 row_mask:0xf bank_mask:0xf bound_ctrl:1
	s_nop 0
	v_readlane_b32 s58, v23, 15
	v_readlane_b32 s71, v23, 31
	v_readlane_b32 s59, v23, 47
	s_and_saveexec_b64 s[4:5], s[8:9]
	s_xor_b64 vcc, exec, s[4:5]
	s_cbranch_execz .LBB0_369
	s_and_saveexec_b64 s[4:5], s[10:11]
	s_xor_b64 s[6:7], exec, s[4:5]
	v_mov_b32_e32 v93, s58
	v_cndmask_b32_e64 v93, 0, v93, s[12:13]
	s_andn2_saveexec_b64 s[6:7], s[6:7]
	v_mov_b32_e32 v93, s71
	v_add_f32_e32 v93, s58, v93
	s_or_b64 exec, exec, s[6:7]
; __device__ __forceinline__ void gla_bcum(const u32x4 a0, const u32x4 a1, const float* wa2, const float* ba, int h, int lane, int wave, float (&bc)[8], float (&bl)[8]) {
;     ...
;     for (int x = 0; x < 4; ++x) { al[2 * x] = __uint_as_float(a0[x] << 16); al[2 * x + 1] = __uint_as_float(a0[x] & 0xffff0000u); al[8 + 2 * x] = __uint_as_float(a1[x] << 16); al[8 + 2 * x + 1] = __uint_as_float(a1[x] & 0xffff0000u); }
; #pragma unroll
;     for (int x = 0; x < 8; ++x) { const int col = h * 64 + 8 * wave + x; float z = ba[col];
; #pragma unroll
;         for (int i = 0; i < 16; ++i) z += al[i] * wa2[i * 256 + col];
;         float la = (fminf(z, 0.f) - __logf(1.f + __expf(-fabsf(z)))) * (1.f / 16.f);
;         la += __builtin_bit_cast(float, __builtin_amdgcn_update_dpp(0, __builtin_bit_cast(int, la), 0x111, 0xf, 0xf, true));
;         la += __builtin_bit_cast(float, __builtin_amdgcn_update_dpp(0, __builtin_bit_cast(int, la), 0x112, 0xf, 0xf, true));
;         la += __builtin_bit_cast(float, __builtin_amdgcn_update_dpp(0, __builtin_bit_cast(int, la), 0x114, 0xf, 0xf, true));
;         la += __builtin_bit_cast(float, __builtin_amdgcn_update_dpp(0, __builtin_bit_cast(int, la), 0x118, 0xf, 0xf, true));
;         const float t0 = __builtin_bit_cast(float, __builtin_amdgcn_readlane(__builtin_bit_cast(int, la), 15)), t1 = __builtin_bit_cast(float, __builtin_amdgcn_readlane(__builtin_bit_cast(int, la), 31)),
;                     t2 = __builtin_bit_cast(float, __builtin_amdgcn_readlane(__builtin_bit_cast(int, la), 47)), t3 = __builtin_bit_cast(float, __builtin_amdgcn_readlane(__builtin_bit_cast(int, la), 63));
;         la += (lane >= 48) ? (t0 + t1) + t2 : (lane >= 32) ? t0 + t1 : (lane >= 16) ? t0 : 0.f;
;         bc[x] = la; bl[x] = ((t0 + t1) + t2) + t3; }
.LBB0_369:
	s_andn2_saveexec_b64 vcc, vcc
	v_mov_b32_e32 v93, s71
	v_add_f32_e32 v93, s58, v93
	v_add_f32_e32 v93, s59, v93
	s_or_b64 exec, exec, vcc
	s_mov_b32 s4, 0xbfb8aa3b
	s_waitcnt lgkmcnt(0)
	v_mov_b32_e32 v94, s82
	v_fmac_f32_e32 v94, s83, v92
	v_fmac_f32_e32 v94, s84, v91
	v_fmac_f32_e32 v94, s85, v90
	v_fmac_f32_e32 v94, s86, v89
	v_fmac_f32_e32 v94, s87, v88
	v_fmac_f32_e32 v94, s88, v31
	v_fmac_f32_e32 v94, s89, v30
	v_fmac_f32_e32 v94, s90, v29
	v_fmac_f32_e32 v94, s91, v28
	v_fmac_f32_e32 v94, s94, v27
	v_fmac_f32_e32 v94, s95, v26
	v_fmac_f32_e32 v94, s96, v25
	v_fmac_f32_e32 v94, s97, v24
	v_fmac_f32_e32 v94, s51, v20
	v_fmac_f32_e32 v94, s52, v19
	v_fmac_f32_e32 v94, s53, v18
	s_load_dword s82, s[76:77], 0x10
	s_load_dword s83, s[48:49], 0x10
	s_load_dword s84, s[48:49], 0x410
	s_load_dword s85, s[48:49], 0x810
	s_load_dword s86, s[48:49], 0xc10
	s_load_dword s87, s[48:49], 0x1010
	s_load_dword s88, s[48:49], 0x1410
	s_load_dword s89, s[48:49], 0x1810
	s_load_dword s90, s[48:49], 0x1c10
	s_load_dword s91, s[48:49], 0x2010
	s_load_dword s94, s[48:49], 0x2410
	s_load_dword s95, s[48:49], 0x2810
	s_load_dword s96, s[48:49], 0x2c10
	s_load_dword s97, s[48:49], 0x3010
	s_load_dword s51, s[48:49], 0x3410
	s_load_dword s52, s[48:49], 0x3810
	s_load_dword s53, s[48:49], 0x3c10
	v_mul_f32_e64 v95, |v94|, s4
	v_exp_f32_e32 v95, v95
	s_mov_b32 s4, 0x3f317217
	v_min_f32_e32 v94, 0, v94
	v_add_f32_e32 v95, 1.0, v95
	v_cmp_gt_f32_e32 vcc, s81, v95
	s_nop 1
	v_cndmask_b32_e64 v96, 0, 32, vcc
	v_ldexp_f32 v95, v95, v96
	v_log_f32_e32 v95, v95
	v_cndmask_b32_e32 v96, 0, v231, vcc
	v_mul_f32_e32 v97, 0x3f317217, v95
	v_fma_f32 v97, v95, s4, -v97
	v_fmac_f32_e32 v97, 0x3377d1cf, v95
	s_mov_b32 s4, 0x7f800000
	v_fmac_f32_e32 v97, 0x3f317217, v95
	v_cmp_lt_f32_e64 vcc, |v95|, s4
	s_nop 1
	v_cndmask_b32_e32 v95, v95, v97, vcc
	v_sub_f32_e32 v95, v95, v96
	v_sub_f32_e32 v94, v94, v95
	v_mul_f32_e32 v95, 0x3d800000, v94
	s_nop 1
	v_mov_b32_dpp v95, v95 row_shr:1 row_mask:0xf bank_mask:0xf bound_ctrl:1
	v_fmac_f32_e32 v95, 0x3d800000, v94
	s_nop 1
	v_add_f32_dpp v94, v95, v95 row_shr:2 row_mask:0xf bank_mask:0xf bound_ctrl:1
	s_nop 1
	v_add_f32_dpp v94, v94, v94 row_shr:4 row_mask:0xf bank_mask:0xf bound_ctrl:1
	s_nop 1
	v_add_f32_dpp v94, v94, v94 row_shr:8 row_mask:0xf bank_mask:0xf bound_ctrl:1
	s_nop 0
	v_readlane_b32 s58, v94, 15
	v_readlane_b32 s71, v94, 31
	v_readlane_b32 s59, v94, 47
	s_and_saveexec_b64 s[4:5], s[8:9]
	s_xor_b64 vcc, exec, s[4:5]
	s_cbranch_execz .LBB0_377
	s_and_saveexec_b64 s[4:5], s[10:11]
	s_xor_b64 s[6:7], exec, s[4:5]
	v_mov_b32_e32 v95, s58
	v_cndmask_b32_e64 v95, 0, v95, s[12:13]
	s_andn2_saveexec_b64 s[6:7], s[6:7]
	v_mov_b32_e32 v95, s71
	v_add_f32_e32 v95, s58, v95
	s_or_b64 exec, exec, s[6:7]
.LBB0_377:
	s_andn2_saveexec_b64 vcc, vcc
	v_mov_b32_e32 v95, s71
	v_add_f32_e32 v95, s58, v95
	v_add_f32_e32 v95, s59, v95
	s_or_b64 exec, exec, vcc
	s_mov_b32 s4, 0xbfb8aa3b
	s_waitcnt lgkmcnt(0)
	v_mov_b32_e32 v96, s82
	v_fmac_f32_e32 v96, s83, v92
	v_fmac_f32_e32 v96, s84, v91
	v_fmac_f32_e32 v96, s85, v90
	v_fmac_f32_e32 v96, s86, v89
	v_fmac_f32_e32 v96, s87, v88
	v_fmac_f32_e32 v96, s88, v31
	v_fmac_f32_e32 v96, s89, v30
	v_fmac_f32_e32 v96, s90, v29
	v_fmac_f32_e32 v96, s91, v28
	v_fmac_f32_e32 v96, s94, v27
	v_fmac_f32_e32 v96, s95, v26
	v_fmac_f32_e32 v96, s96, v25
	v_fmac_f32_e32 v96, s97, v24
	v_fmac_f32_e32 v96, s51, v20
	v_fmac_f32_e32 v96, s52, v19
	v_fmac_f32_e32 v96, s53, v18
	s_load_dword s82, s[76:77], 0x14
	s_load_dword s83, s[48:49], 0x14
	s_load_dword s84, s[48:49], 0x414
	s_load_dword s85, s[48:49], 0x814
	s_load_dword s86, s[48:49], 0xc14
	s_load_dword s87, s[48:49], 0x1014
	s_load_dword s88, s[48:49], 0x1414
	s_load_dword s89, s[48:49], 0x1814
	s_load_dword s90, s[48:49], 0x1c14
	s_load_dword s91, s[48:49], 0x2014
	s_load_dword s94, s[48:49], 0x2414
	s_load_dword s95, s[48:49], 0x2814
	s_load_dword s96, s[48:49], 0x2c14
	s_load_dword s97, s[48:49], 0x3014
	s_load_dword s51, s[48:49], 0x3414
	s_load_dword s52, s[48:49], 0x3814
	s_load_dword s53, s[48:49], 0x3c14
	v_mul_f32_e64 v97, |v96|, s4
	v_exp_f32_e32 v97, v97
	s_mov_b32 s4, 0x3f317217
	v_min_f32_e32 v96, 0, v96
	v_add_f32_e32 v97, 1.0, v97
	v_cmp_gt_f32_e32 vcc, s81, v97
	s_nop 1
	v_cndmask_b32_e64 v98, 0, 32, vcc
	v_ldexp_f32 v97, v97, v98
	v_log_f32_e32 v97, v97
	v_cndmask_b32_e32 v98, 0, v231, vcc
	v_mul_f32_e32 v99, 0x3f317217, v97
	v_fma_f32 v99, v97, s4, -v99
	v_fmac_f32_e32 v99, 0x3377d1cf, v97
	s_mov_b32 s4, 0x7f800000
	v_fmac_f32_e32 v99, 0x3f317217, v97
	v_cmp_lt_f32_e64 vcc, |v97|, s4
	s_nop 1
	v_cndmask_b32_e32 v97, v97, v99, vcc
	v_sub_f32_e32 v97, v97, v98
	v_sub_f32_e32 v96, v96, v97
	v_mul_f32_e32 v97, 0x3d800000, v96
	s_nop 1
	v_mov_b32_dpp v97, v97 row_shr:1 row_mask:0xf bank_mask:0xf bound_ctrl:1
	v_fmac_f32_e32 v97, 0x3d800000, v96
	s_nop 1
	v_add_f32_dpp v96, v97, v97 row_shr:2 row_mask:0xf bank_mask:0xf bound_ctrl:1
	s_nop 1
	v_add_f32_dpp v96, v96, v96 row_shr:4 row_mask:0xf bank_mask:0xf bound_ctrl:1
	s_nop 1
	v_add_f32_dpp v96, v96, v96 row_shr:8 row_mask:0xf bank_mask:0xf bound_ctrl:1
	s_nop 0
	v_readlane_b32 s58, v96, 15
	v_readlane_b32 s71, v96, 31
	v_readlane_b32 s59, v96, 47
	s_and_saveexec_b64 s[4:5], s[8:9]
	s_xor_b64 vcc, exec, s[4:5]
	s_cbranch_execz .LBB0_385
	s_and_saveexec_b64 s[4:5], s[10:11]
	s_xor_b64 s[6:7], exec, s[4:5]
	v_mov_b32_e32 v97, s58
	v_cndmask_b32_e64 v97, 0, v97, s[12:13]
	s_andn2_saveexec_b64 s[6:7], s[6:7]
	v_mov_b32_e32 v97, s71
	v_add_f32_e32 v97, s58, v97
	s_or_b64 exec, exec, s[6:7]
; __device__ __forceinline__ void gla_bcum(const u32x4 a0, const u32x4 a1, const float* wa2, const float* ba, int h, int lane, int wave, float (&bc)[8], float (&bl)[8]) {
;     ...
;     for (int x = 0; x < 4; ++x) { al[2 * x] = __uint_as_float(a0[x] << 16); al[2 * x + 1] = __uint_as_float(a0[x] & 0xffff0000u); al[8 + 2 * x] = __uint_as_float(a1[x] << 16); al[8 + 2 * x + 1] = __uint_as_float(a1[x] & 0xffff0000u); }
; #pragma unroll
;     for (int x = 0; x < 8; ++x) { const int col = h * 64 + 8 * wave + x; float z = ba[col];
; #pragma unroll
;         for (int i = 0; i < 16; ++i) z += al[i] * wa2[i * 256 + col];
;         float la = (fminf(z, 0.f) - __logf(1.f + __expf(-fabsf(z)))) * (1.f / 16.f);
;         la += __builtin_bit_cast(float, __builtin_amdgcn_update_dpp(0, __builtin_bit_cast(int, la), 0x111, 0xf, 0xf, true));
;         la += __builtin_bit_cast(float, __builtin_amdgcn_update_dpp(0, __builtin_bit_cast(int, la), 0x112, 0xf, 0xf, true));
;         la += __builtin_bit_cast(float, __builtin_amdgcn_update_dpp(0, __builtin_bit_cast(int, la), 0x114, 0xf, 0xf, true));
;         la += __builtin_bit_cast(float, __builtin_amdgcn_update_dpp(0, __builtin_bit_cast(int, la), 0x118, 0xf, 0xf, true));
;         const float t0 = __builtin_bit_cast(float, __builtin_amdgcn_readlane(__builtin_bit_cast(int, la), 15)), t1 = __builtin_bit_cast(float, __builtin_amdgcn_readlane(__builtin_bit_cast(int, la), 31)),
;                     t2 = __builtin_bit_cast(float, __builtin_amdgcn_readlane(__builtin_bit_cast(int, la), 47)), t3 = __builtin_bit_cast(float, __builtin_amdgcn_readlane(__builtin_bit_cast(int, la), 63));
;         la += (lane >= 48) ? (t0 + t1) + t2 : (lane >= 32) ? t0 + t1 : (lane >= 16) ? t0 : 0.f;
;         bc[x] = la; bl[x] = ((t0 + t1) + t2) + t3; }
.LBB0_385:
	s_andn2_saveexec_b64 vcc, vcc
	v_mov_b32_e32 v97, s71
	v_add_f32_e32 v97, s58, v97
	v_add_f32_e32 v97, s59, v97
	s_or_b64 exec, exec, vcc
	s_mov_b32 s4, 0xbfb8aa3b
	s_waitcnt lgkmcnt(0)
	v_mov_b32_e32 v98, s82
	v_fmac_f32_e32 v98, s83, v92
	v_fmac_f32_e32 v98, s84, v91
	v_fmac_f32_e32 v98, s85, v90
	v_fmac_f32_e32 v98, s86, v89
	v_fmac_f32_e32 v98, s87, v88
	v_fmac_f32_e32 v98, s88, v31
	v_fmac_f32_e32 v98, s89, v30
	v_fmac_f32_e32 v98, s90, v29
	v_fmac_f32_e32 v98, s91, v28
	v_fmac_f32_e32 v98, s94, v27
	v_fmac_f32_e32 v98, s95, v26
	v_fmac_f32_e32 v98, s96, v25
	v_fmac_f32_e32 v98, s97, v24
	v_fmac_f32_e32 v98, s51, v20
	v_fmac_f32_e32 v98, s52, v19
	v_fmac_f32_e32 v98, s53, v18
	s_load_dword s82, s[76:77], 0x18
	s_load_dword s83, s[48:49], 0x18
	s_load_dword s84, s[48:49], 0x418
	s_load_dword s85, s[48:49], 0x818
	s_load_dword s86, s[48:49], 0xc18
	s_load_dword s87, s[48:49], 0x1018
	s_load_dword s88, s[48:49], 0x1418
	s_load_dword s89, s[48:49], 0x1818
	s_load_dword s90, s[48:49], 0x1c18
	s_load_dword s91, s[48:49], 0x2018
	s_load_dword s94, s[48:49], 0x2418
	s_load_dword s95, s[48:49], 0x2818
	s_load_dword s96, s[48:49], 0x2c18
	s_load_dword s97, s[48:49], 0x3018
	s_load_dword s51, s[48:49], 0x3418
	s_load_dword s52, s[48:49], 0x3818
	s_load_dword s53, s[48:49], 0x3c18
	v_mul_f32_e64 v99, |v98|, s4
	v_exp_f32_e32 v99, v99
	s_mov_b32 s4, 0x3f317217
	v_min_f32_e32 v98, 0, v98
	v_add_f32_e32 v99, 1.0, v99
	v_cmp_gt_f32_e32 vcc, s81, v99
	s_nop 1
	v_cndmask_b32_e64 v100, 0, 32, vcc
	v_ldexp_f32 v99, v99, v100
	v_log_f32_e32 v99, v99
	v_cndmask_b32_e32 v100, 0, v231, vcc
	v_mul_f32_e32 v101, 0x3f317217, v99
	v_fma_f32 v101, v99, s4, -v101
	v_fmac_f32_e32 v101, 0x3377d1cf, v99
	s_mov_b32 s4, 0x7f800000
	v_fmac_f32_e32 v101, 0x3f317217, v99
	v_cmp_lt_f32_e64 vcc, |v99|, s4
	s_nop 1
	v_cndmask_b32_e32 v99, v99, v101, vcc
	v_sub_f32_e32 v99, v99, v100
	v_sub_f32_e32 v98, v98, v99
	v_mul_f32_e32 v99, 0x3d800000, v98
	s_nop 1
	v_mov_b32_dpp v99, v99 row_shr:1 row_mask:0xf bank_mask:0xf bound_ctrl:1
	v_fmac_f32_e32 v99, 0x3d800000, v98
	s_nop 1
	v_add_f32_dpp v98, v99, v99 row_shr:2 row_mask:0xf bank_mask:0xf bound_ctrl:1
	s_nop 1
	v_add_f32_dpp v98, v98, v98 row_shr:4 row_mask:0xf bank_mask:0xf bound_ctrl:1
	s_nop 1
	v_add_f32_dpp v98, v98, v98 row_shr:8 row_mask:0xf bank_mask:0xf bound_ctrl:1
	s_nop 0
	v_readlane_b32 s58, v98, 15
	v_readlane_b32 s71, v98, 31
	v_readlane_b32 s59, v98, 47
	s_and_saveexec_b64 s[4:5], s[8:9]
	s_xor_b64 vcc, exec, s[4:5]
	s_cbranch_execz .LBB0_393
	s_and_saveexec_b64 s[4:5], s[10:11]
	s_xor_b64 s[6:7], exec, s[4:5]
	v_mov_b32_e32 v99, s58
	v_cndmask_b32_e64 v99, 0, v99, s[12:13]
	s_andn2_saveexec_b64 s[6:7], s[6:7]
	v_mov_b32_e32 v99, s71
	v_add_f32_e32 v99, s58, v99
	s_or_b64 exec, exec, s[6:7]
; __device__ __forceinline__ void gla_bcum(const u32x4 a0, const u32x4 a1, const float* wa2, const float* ba, int h, int lane, int wave, float (&bc)[8], float (&bl)[8]) {
;     ...
;     for (int x = 0; x < 4; ++x) { al[2 * x] = __uint_as_float(a0[x] << 16); al[2 * x + 1] = __uint_as_float(a0[x] & 0xffff0000u); al[8 + 2 * x] = __uint_as_float(a1[x] << 16); al[8 + 2 * x + 1] = __uint_as_float(a1[x] & 0xffff0000u); }
; #pragma unroll
;     for (int x = 0; x < 8; ++x) { const int col = h * 64 + 8 * wave + x; float z = ba[col];
; #pragma unroll
;         for (int i = 0; i < 16; ++i) z += al[i] * wa2[i * 256 + col];
;         float la = (fminf(z, 0.f) - __logf(1.f + __expf(-fabsf(z)))) * (1.f / 16.f);
;         la += __builtin_bit_cast(float, __builtin_amdgcn_update_dpp(0, __builtin_bit_cast(int, la), 0x111, 0xf, 0xf, true));
;         la += __builtin_bit_cast(float, __builtin_amdgcn_update_dpp(0, __builtin_bit_cast(int, la), 0x112, 0xf, 0xf, true));
;         la += __builtin_bit_cast(float, __builtin_amdgcn_update_dpp(0, __builtin_bit_cast(int, la), 0x114, 0xf, 0xf, true));
;         la += __builtin_bit_cast(float, __builtin_amdgcn_update_dpp(0, __builtin_bit_cast(int, la), 0x118, 0xf, 0xf, true));
;         const float t0 = __builtin_bit_cast(float, __builtin_amdgcn_readlane(__builtin_bit_cast(int, la), 15)), t1 = __builtin_bit_cast(float, __builtin_amdgcn_readlane(__builtin_bit_cast(int, la), 31)),
;                     t2 = __builtin_bit_cast(float, __builtin_amdgcn_readlane(__builtin_bit_cast(int, la), 47)), t3 = __builtin_bit_cast(float, __builtin_amdgcn_readlane(__builtin_bit_cast(int, la), 63));
;         la += (lane >= 48) ? (t0 + t1) + t2 : (lane >= 32) ? t0 + t1 : (lane >= 16) ? t0 : 0.f;
;         bc[x] = la; bl[x] = ((t0 + t1) + t2) + t3; }
.LBB0_393:
	s_andn2_saveexec_b64 vcc, vcc
	v_mov_b32_e32 v99, s71
	v_add_f32_e32 v99, s58, v99
	v_add_f32_e32 v99, s59, v99
	s_or_b64 exec, exec, vcc
	s_mov_b32 s4, 0xbfb8aa3b
	s_waitcnt lgkmcnt(0)
	v_mov_b32_e32 v100, s82
	v_fmac_f32_e32 v100, s83, v92
	v_fmac_f32_e32 v100, s84, v91
	v_fmac_f32_e32 v100, s85, v90
	v_fmac_f32_e32 v100, s86, v89
	v_fmac_f32_e32 v100, s87, v88
	v_fmac_f32_e32 v100, s88, v31
	v_fmac_f32_e32 v100, s89, v30
	v_fmac_f32_e32 v100, s90, v29
	v_fmac_f32_e32 v100, s91, v28
	v_fmac_f32_e32 v100, s94, v27
	v_fmac_f32_e32 v100, s95, v26
	v_fmac_f32_e32 v100, s96, v25
	v_fmac_f32_e32 v100, s97, v24
	v_fmac_f32_e32 v100, s51, v20
	v_fmac_f32_e32 v100, s52, v19
	v_fmac_f32_e32 v100, s53, v18
	s_load_dword s82, s[76:77], 0x1c
	s_load_dword s83, s[48:49], 0x1c
	s_load_dword s84, s[48:49], 0x41c
	s_load_dword s85, s[48:49], 0x81c
	s_load_dword s86, s[48:49], 0xc1c
	s_load_dword s87, s[48:49], 0x101c
	s_load_dword s88, s[48:49], 0x141c
	s_load_dword s89, s[48:49], 0x181c
	s_load_dword s90, s[48:49], 0x1c1c
	s_load_dword s91, s[48:49], 0x201c
	s_load_dword s94, s[48:49], 0x241c
	s_load_dword s95, s[48:49], 0x281c
	s_load_dword s96, s[48:49], 0x2c1c
	s_load_dword s97, s[48:49], 0x301c
	s_load_dword s51, s[48:49], 0x341c
	s_load_dword s52, s[48:49], 0x381c
	s_load_dword s53, s[48:49], 0x3c1c
	v_mul_f32_e64 v101, |v100|, s4
	v_exp_f32_e32 v101, v101
	s_mov_b32 s4, 0x3f317217
	v_min_f32_e32 v100, 0, v100
	v_add_f32_e32 v101, 1.0, v101
	v_cmp_gt_f32_e32 vcc, s81, v101
	s_nop 1
	v_cndmask_b32_e64 v102, 0, 32, vcc
	v_ldexp_f32 v101, v101, v102
	v_log_f32_e32 v101, v101
	v_cndmask_b32_e32 v102, 0, v231, vcc
	v_mul_f32_e32 v103, 0x3f317217, v101
	v_fma_f32 v103, v101, s4, -v103
	v_fmac_f32_e32 v103, 0x3377d1cf, v101
	s_mov_b32 s4, 0x7f800000
	v_fmac_f32_e32 v103, 0x3f317217, v101
	v_cmp_lt_f32_e64 vcc, |v101|, s4
	s_nop 1
	v_cndmask_b32_e32 v101, v101, v103, vcc
	v_sub_f32_e32 v101, v101, v102
	v_sub_f32_e32 v100, v100, v101
	v_mul_f32_e32 v101, 0x3d800000, v100
	s_nop 1
	v_mov_b32_dpp v101, v101 row_shr:1 row_mask:0xf bank_mask:0xf bound_ctrl:1
	v_fmac_f32_e32 v101, 0x3d800000, v100
	s_nop 1
	v_add_f32_dpp v100, v101, v101 row_shr:2 row_mask:0xf bank_mask:0xf bound_ctrl:1
	s_nop 1
	v_add_f32_dpp v100, v100, v100 row_shr:4 row_mask:0xf bank_mask:0xf bound_ctrl:1
	s_nop 1
	v_add_f32_dpp v100, v100, v100 row_shr:8 row_mask:0xf bank_mask:0xf bound_ctrl:1
	s_nop 0
	v_readlane_b32 s58, v100, 15
	v_readlane_b32 s71, v100, 31
	v_readlane_b32 s59, v100, 47
	s_and_saveexec_b64 s[4:5], s[8:9]
	s_xor_b64 vcc, exec, s[4:5]
	s_cbranch_execz .LBB0_401
	s_and_saveexec_b64 s[4:5], s[10:11]
	s_xor_b64 s[6:7], exec, s[4:5]
	v_mov_b32_e32 v101, s58
	v_cndmask_b32_e64 v101, 0, v101, s[12:13]
	s_andn2_saveexec_b64 s[6:7], s[6:7]
	v_mov_b32_e32 v101, s71
	v_add_f32_e32 v101, s58, v101
	s_or_b64 exec, exec, s[6:7]
.LBB0_401:
	s_andn2_saveexec_b64 vcc, vcc
	v_mov_b32_e32 v101, s71
	v_add_f32_e32 v101, s58, v101
	v_add_f32_e32 v101, s59, v101
	s_or_b64 exec, exec, vcc
	s_mov_b32 s4, 0xbfb8aa3b
	s_waitcnt lgkmcnt(0)
	v_mov_b32_e32 v102, s82
	v_fmac_f32_e32 v102, s83, v92
	v_fmac_f32_e32 v102, s84, v91
	v_fmac_f32_e32 v102, s85, v90
	v_fmac_f32_e32 v102, s86, v89
	v_fmac_f32_e32 v102, s87, v88
	v_fmac_f32_e32 v102, s88, v31
	v_fmac_f32_e32 v102, s89, v30
	v_fmac_f32_e32 v102, s90, v29
	v_fmac_f32_e32 v102, s91, v28
	v_fmac_f32_e32 v102, s94, v27
	v_fmac_f32_e32 v102, s95, v26
	v_fmac_f32_e32 v102, s96, v25
	v_fmac_f32_e32 v102, s97, v24
	v_fmac_f32_e32 v102, s51, v20
	v_fmac_f32_e32 v102, s52, v19
	v_fmac_f32_e32 v102, s53, v18
	v_readlane_b32 s82, v255, 29
	v_readlane_b32 s83, v255, 30
	v_readlane_b32 s84, v255, 31
	v_readlane_b32 s85, v255, 32
	v_readlane_b32 s86, v255, 33
	v_readlane_b32 s87, v255, 34
	v_readlane_b32 s88, v255, 35
	v_readlane_b32 s89, v255, 36
	v_readlane_b32 s90, v255, 37
	v_readlane_b32 s91, v255, 38
	v_readlane_b32 s94, v255, 39
	v_readlane_b32 s95, v255, 40
	v_readlane_b32 s96, v255, 41
	v_readlane_b32 s97, v255, 42
	v_readlane_b32 s51, v255, 43
	v_readlane_b32 s52, v255, 44
	v_readlane_b32 s53, v255, 45
	s_waitcnt vmcnt(0)
	v_mul_f32_e64 v19, |v102|, s4
	v_exp_f32_e32 v19, v19
	s_mov_b32 s4, 0x3f317217
	v_min_f32_e32 v18, 0, v102
	v_add_f32_e32 v19, 1.0, v19
	v_cmp_gt_f32_e32 vcc, s81, v19
	s_nop 1
	v_cndmask_b32_e64 v20, 0, 32, vcc
	v_ldexp_f32 v19, v19, v20
	v_log_f32_e32 v19, v19
	s_nop 0
	v_mul_f32_e32 v20, 0x3f317217, v19
	v_fma_f32 v20, v19, s4, -v20
	v_fmac_f32_e32 v20, 0x3377d1cf, v19
	s_mov_b32 s4, 0x7f800000
	v_fmac_f32_e32 v20, 0x3f317217, v19
	v_cmp_lt_f32_e64 s[48:49], |v19|, s4
	s_nop 1
	v_cndmask_b32_e64 v19, v19, v20, s[48:49]
	v_cndmask_b32_e32 v20, 0, v231, vcc
	v_sub_f32_e32 v19, v19, v20
	v_sub_f32_e32 v18, v18, v19
	v_mul_f32_e32 v19, 0x3d800000, v18
	s_nop 1
	v_mov_b32_dpp v19, v19 row_shr:1 row_mask:0xf bank_mask:0xf bound_ctrl:1
	v_fmac_f32_e32 v19, 0x3d800000, v18
	s_nop 1
	v_add_f32_dpp v18, v19, v19 row_shr:2 row_mask:0xf bank_mask:0xf bound_ctrl:1
	s_nop 1
	v_add_f32_dpp v18, v18, v18 row_shr:4 row_mask:0xf bank_mask:0xf bound_ctrl:1
	s_nop 1
	v_add_f32_dpp v18, v18, v18 row_shr:8 row_mask:0xf bank_mask:0xf bound_ctrl:1
	s_nop 0
	v_readlane_b32 s58, v18, 15
	v_readlane_b32 s71, v18, 31
	v_readlane_b32 s59, v18, 47
	s_and_saveexec_b64 s[4:5], s[8:9]
	s_xor_b64 s[48:49], exec, s[4:5]
	s_cbranch_execz .LBB0_409
	s_and_saveexec_b64 s[4:5], s[10:11]
	s_xor_b64 s[6:7], exec, s[4:5]
	v_mov_b32_e32 v19, s58
	v_cndmask_b32_e64 v19, 0, v19, s[12:13]
	s_andn2_saveexec_b64 s[6:7], s[6:7]
	v_mov_b32_e32 v19, s71
	v_add_f32_e32 v19, s58, v19
	s_or_b64 exec, exec, s[6:7]

; __device__ __forceinline__ bf16_t f2bf(float f) { unsigned u = __float_as_uint(f); return (bf16_t)((u + 0x7fffu + ((u >> 16) & 1u)) >> 16); }
; #define LAS __attribute__((address_space(3)))
; #define GLA_BAR() do { asm volatile("s_waitcnt lgkmcnt(0)" ::: "memory"); __builtin_amdgcn_s_barrier(); asm volatile("" ::: "memory"); } while (0)
; __device__ __forceinline__ void gla_g1_phase(LAS unsigned char* lds, const bf16_t* PROJ, const bf16_t* ALOW, const float* wa2, const float* ba, float* UPD, float* DEC, int G, int tid) {
;     LAS bf16_t* KD = (LAS bf16_t*)lds; LAS bf16_t* VT = (LAS bf16_t*)(lds + 18432);
;     const int lane = tid & 63, wave = __builtin_amdgcn_readfirstlane(tid >> 6);
;     G1In cur; if ((int)blockIdx.x < 2048) cur = g1_load(PROJ, ALOW, blockIdx.x, lane, wave);
;     for (int u = blockIdx.x; u < 2048; u += G) {
;         G1In nxt; if (u + G < 2048) nxt = g1_load(PROJ, ALOW, u + G, lane, wave);
;         const int bh = u >> 7, h = bh & 3;
;         float bc[8], bl[8];
;         gla_bcum(cur.a0, cur.a1, wa2, ba, h, lane, wave, bc, bl);
;         float kf[8]; unpack8(cur.k, kf);
; #pragma unroll
;         for (int x = 0; x < 8; ++x) KD[(8 * wave + x) * GP + lane] = f2bf(kf[x] * __expf(bl[x] - bc[x]));
;         if (lane == 63) {
; #pragma unroll
;             for (int x = 0; x < 8; ++x) DEC[u * 64 + 8 * wave + x] = __expf(bl[x]); }
; #pragma unroll
;         for (int pc = 0; pc < 2; ++pc) { const int e0 = 64 * pc + 8 * wave; const u32x4 v = pc ? cur.v1 : cur.v0;
; #pragma unroll
;             for (int x = 0; x < 4; ++x) { VT[(e0 + 2 * x) * GP + lane] = (bf16_t)(v[x] & 0xffffu); VT[(e0 + 2 * x + 1) * GP + lane] = (bf16_t)(v[x] >> 16); } }
;         GLA_BAR();
;         const int eb = wave >> 1, dbk = wave & 1, i = lane & 31, kg = lane >> 5;
.LBB0_468:
	s_and_b64 vcc, exec, s[8:9]
	s_cbranch_vccnz .LBB0_539
	s_load_dwordx2 s[4:5], s[4:5], 0x0
	s_nop 0
	s_load_dwordx2 s[8:9], s[10:11], 0x0
	v_readlane_b32 s10, v253, 47
	v_readlane_b32 s11, v253, 48
	s_lshl_b64 s[10:11], s[10:11], 2
	s_waitcnt lgkmcnt(0)
	s_add_u32 s26, s4, s10
	s_addc_u32 s27, s5, s11
	v_readlane_b32 s4, v253, 49
	v_readlane_b32 s5, v253, 50
	s_lshl_b64 s[4:5], s[4:5], 2
	s_add_u32 s28, s8, s4
	s_addc_u32 s29, s9, s5
	s_ashr_i32 s17, s6, 2
	s_and_b32 s16, s17, 0xffffffe0
	v_mov_b32_e32 v19, s17
	s_movk_i32 s17, 0xffe0
	v_bfi_b32 v19, s17, v19, v170
	s_movk_i32 s17, 0x90
	v_lshrrev_b32_e32 v20, 1, v172
	s_lshl_b32 s4, s7, 3
	v_and_b32_e32 v17, 31, v170
	v_mul_lo_u32 v19, v19, s17
	v_and_b32_e32 v20, 16, v20
	s_lshl_b32 s17, s7, 5
	s_mulk_i32 s7, 0x480
	v_lshlrev_b32_e32 v16, 1, v172
	v_add3_u32 v42, 0, v19, v20
	v_and_or_b32 v19, s17, 32, v17
	s_ashr_i32 s17, s16, 31
	s_add_i32 s18, s7, 0
	v_add_u32_e32 v18, 0, v16
	v_add_u32_e32 v44, s18, v16
	v_and_b32_e32 v16, 32, v170
	s_lshl_b64 s[16:17], s[16:17], 8
	s_lshl_b32 s6, s6, 1
	v_lshl_or_b32 v16, v16, 5, s16
	s_and_b32 s6, s6, 0x80
	v_lshlrev_b32_e32 v17, 2, v17
	v_or3_b32 v16, v16, s6, v17
	v_mov_b32_e32 v17, s17
	v_readlane_b32 s16, v253, 23
	v_mul_u32_u24_e32 v19, 0x90, v19
	v_readlane_b32 s17, v253, 24
	s_ashr_i32 s5, s4, 31
	v_cmp_gt_u32_e64 s[8:9], 48, v172
	v_cmp_gt_u32_e64 s[10:11], 32, v172
	v_cmp_lt_u32_e64 s[12:13], 15, v172
	v_cmp_eq_u32_e64 s[14:15], 63, v172
	v_add3_u32 v43, 0, v19, v20
	v_lshl_add_u64 v[40:41], s[16:17], 0, v[16:17]
	v_add_u32_e32 v45, s7, v18
	v_readlane_b32 s30, v253, 25
	v_readlane_b32 s31, v250, 52
	s_mov_b32 s6, s2
	s_waitcnt vmcnt(0)
	s_branch .LBB0_471

; __device__ __forceinline__ void gla_bcum(const u32x4 a0, const u32x4 a1, const float* wa2, const float* ba, int h, int lane, int wave, float (&bc)[8], float (&bl)[8]) {
;     float al[16];
; #pragma unroll
;     for (int x = 0; x < 4; ++x) { al[2 * x] = __uint_as_float(a0[x] << 16); al[2 * x + 1] = __uint_as_float(a0[x] & 0xffff0000u); al[8 + 2 * x] = __uint_as_float(a1[x] << 16); al[8 + 2 * x + 1] = __uint_as_float(a1[x] & 0xffff0000u); }
; #pragma unroll
;     for (int x = 0; x < 8; ++x) { const int col = h * 64 + 8 * wave + x; float z = ba[col];
; #pragma unroll
;         for (int i = 0; i < 16; ++i) z += al[i] * wa2[i * 256 + col];
;         float la = (fminf(z, 0.f) - __logf(1.f + __expf(-fabsf(z)))) * (1.f / 16.f);
;         la += __builtin_bit_cast(float, __builtin_amdgcn_update_dpp(0, __builtin_bit_cast(int, la), 0x111, 0xf, 0xf, true));
;         la += __builtin_bit_cast(float, __builtin_amdgcn_update_dpp(0, __builtin_bit_cast(int, la), 0x112, 0xf, 0xf, true));
;         la += __builtin_bit_cast(float, __builtin_amdgcn_update_dpp(0, __builtin_bit_cast(int, la), 0x114, 0xf, 0xf, true));
;         la += __builtin_bit_cast(float, __builtin_amdgcn_update_dpp(0, __builtin_bit_cast(int, la), 0x118, 0xf, 0xf, true));
;         const float t0 = __builtin_bit_cast(float, __builtin_amdgcn_readlane(__builtin_bit_cast(int, la), 15)), t1 = __builtin_bit_cast(float, __builtin_amdgcn_readlane(__builtin_bit_cast(int, la), 31)),
;                     t2 = __builtin_bit_cast(float, __builtin_amdgcn_readlane(__builtin_bit_cast(int, la), 47)), t3 = __builtin_bit_cast(float, __builtin_amdgcn_readlane(__builtin_bit_cast(int, la), 63));
;         la += (lane >= 48) ? (t0 + t1) + t2 : (lane >= 32) ? t0 + t1 : (lane >= 16) ? t0 : 0.f;
;         bc[x] = la; bl[x] = ((t0 + t1) + t2) + t3; }
.LBB0_473:
	s_lshr_b32 s6, s6, 1
	s_and_b32 s6, s6, 0xc0
	s_add_i32 s6, s6, s4
	s_ashr_i32 s7, s6, 31
	s_lshl_b64 s[6:7], s[6:7], 2
	s_add_u32 s20, s28, s6
	s_addc_u32 s21, s29, s7
	s_add_u32 s16, s26, s6
	s_addc_u32 s17, s27, s7
	v_writelane_b32 v255, s82, 29
	v_writelane_b32 v255, s83, 30
	v_writelane_b32 v255, s84, 31
	v_writelane_b32 v255, s85, 32
	v_writelane_b32 v255, s86, 33
	v_writelane_b32 v255, s87, 34
	v_writelane_b32 v255, s88, 35
	v_writelane_b32 v255, s89, 36
	v_writelane_b32 v255, s90, 37
	v_writelane_b32 v255, s91, 38
	v_writelane_b32 v255, s94, 39
	v_writelane_b32 v255, s95, 40
	v_writelane_b32 v255, s96, 41
	v_writelane_b32 v255, s97, 42
	v_writelane_b32 v255, s51, 43
	v_writelane_b32 v255, s52, 44
	v_writelane_b32 v255, s53, 45
	s_load_dword s82, s[20:21], 0x0
	s_load_dword s83, s[16:17], 0x0
	s_load_dword s84, s[16:17], 0x400
	s_load_dword s85, s[16:17], 0x800
	s_load_dword s86, s[16:17], 0xc00
	s_load_dword s87, s[16:17], 0x1000
	s_load_dword s88, s[16:17], 0x1400
	s_load_dword s89, s[16:17], 0x1800
	s_load_dword s90, s[16:17], 0x1c00
	s_load_dword s91, s[16:17], 0x2000
	s_load_dword s94, s[16:17], 0x2400
	s_load_dword s95, s[16:17], 0x2800
	s_load_dword s96, s[16:17], 0x2c00
	s_load_dword s97, s[16:17], 0x3000
	s_load_dword s51, s[16:17], 0x3400
	s_load_dword s52, s[16:17], 0x3800
	s_load_dword s53, s[16:17], 0x3c00
	v_lshlrev_b32_e32 v59, 16, v36
	v_and_b32_e32 v58, 0xffff0000, v36
	v_lshlrev_b32_e32 v57, 16, v37
	v_and_b32_e32 v56, 0xffff0000, v37
	v_lshlrev_b32_e32 v55, 16, v38
	v_and_b32_e32 v54, 0xffff0000, v38
	v_lshlrev_b32_e32 v53, 16, v39
	v_and_b32_e32 v52, 0xffff0000, v39
	v_lshlrev_b32_e32 v51, 16, v12
	v_and_b32_e32 v50, 0xffff0000, v12
	v_lshlrev_b32_e32 v49, 16, v13
	v_and_b32_e32 v47, 0xffff0000, v13
	v_lshlrev_b32_e32 v46, 16, v14
	v_and_b32_e32 v38, 0xffff0000, v14
	v_lshlrev_b32_e32 v37, 16, v15
	v_and_b32_e32 v15, 0xffff0000, v15
	s_mov_b32 s6, 0xbfb8aa3b
	s_waitcnt lgkmcnt(0)
	v_mov_b32_e32 v48, s82
	v_fmac_f32_e32 v48, s83, v59
	v_fmac_f32_e32 v48, s84, v58
	v_fmac_f32_e32 v48, s85, v57
	v_fmac_f32_e32 v48, s86, v56
	v_fmac_f32_e32 v48, s87, v55
	v_fmac_f32_e32 v48, s88, v54
	v_fmac_f32_e32 v48, s89, v53
	v_fmac_f32_e32 v48, s90, v52
	v_fmac_f32_e32 v48, s91, v51
	v_fmac_f32_e32 v48, s94, v50
	v_fmac_f32_e32 v48, s95, v49
	v_fmac_f32_e32 v48, s96, v47
	v_fmac_f32_e32 v48, s97, v46
	v_fmac_f32_e32 v48, s51, v38
	v_fmac_f32_e32 v48, s52, v37
	v_fmac_f32_e32 v48, s53, v15
	s_load_dword s82, s[20:21], 0x4
	s_load_dword s83, s[16:17], 0x4
	s_load_dword s84, s[16:17], 0x404
	s_load_dword s85, s[16:17], 0x804
	s_load_dword s86, s[16:17], 0xc04
	s_load_dword s87, s[16:17], 0x1004
	s_load_dword s88, s[16:17], 0x1404
	s_load_dword s89, s[16:17], 0x1804
	s_load_dword s90, s[16:17], 0x1c04
	s_load_dword s91, s[16:17], 0x2004
	s_load_dword s94, s[16:17], 0x2404
	s_load_dword s95, s[16:17], 0x2804
	s_load_dword s96, s[16:17], 0x2c04
	s_load_dword s97, s[16:17], 0x3004
	s_load_dword s51, s[16:17], 0x3404
	s_load_dword s52, s[16:17], 0x3804
	s_load_dword s53, s[16:17], 0x3c04
	v_mul_f32_e64 v12, |v48|, s6
	v_exp_f32_e32 v12, v12
	s_mov_b32 s6, 0x3f317217
	v_add_f32_e32 v12, 1.0, v12
	v_cmp_gt_f32_e32 vcc, s81, v12
	s_nop 1
	v_cndmask_b32_e64 v13, 0, 32, vcc
	v_ldexp_f32 v12, v12, v13
	v_log_f32_e32 v12, v12
	v_cndmask_b32_e32 v14, 0, v231, vcc
	v_min_f32_e32 v13, 0, v48
	v_mul_f32_e32 v36, 0x3f317217, v12
	v_fma_f32 v36, v12, s6, -v36
	v_fmac_f32_e32 v36, 0x3377d1cf, v12
	s_mov_b32 s6, 0x7f800000
	v_fmac_f32_e32 v36, 0x3f317217, v12
	v_cmp_lt_f32_e64 vcc, |v12|, s6
	s_nop 1
	v_cndmask_b32_e32 v12, v12, v36, vcc
	v_sub_f32_e32 v12, v12, v14
	v_sub_f32_e32 v12, v13, v12
	v_mul_f32_e32 v13, 0x3d800000, v12
	s_nop 1
	v_mov_b32_dpp v13, v13 row_shr:1 row_mask:0xf bank_mask:0xf bound_ctrl:1
	v_fmac_f32_e32 v13, 0x3d800000, v12
	s_nop 1
	v_add_f32_dpp v12, v13, v13 row_shr:2 row_mask:0xf bank_mask:0xf bound_ctrl:1
	s_nop 1
	v_add_f32_dpp v12, v12, v12 row_shr:4 row_mask:0xf bank_mask:0xf bound_ctrl:1
	s_nop 1
	v_add_f32_dpp v12, v12, v12 row_shr:8 row_mask:0xf bank_mask:0xf bound_ctrl:1
	s_nop 0
	v_readlane_b32 s6, v12, 15
	v_readlane_b32 s7, v12, 31
	v_readlane_b32 s35, v12, 47
	v_readlane_b32 s36, v12, 63
	s_and_saveexec_b64 s[22:23], s[8:9]
	s_xor_b64 s[22:23], exec, s[22:23]
	s_cbranch_execz .LBB0_479
	s_and_saveexec_b64 s[24:25], s[10:11]
	s_xor_b64 s[24:25], exec, s[24:25]
	v_mov_b32_e32 v13, s6
	v_mov_b32_e32 v14, s7
	v_cndmask_b32_e64 v13, 0, v13, s[12:13]
	v_add_f32_e32 v14, s6, v14
	s_andn2_saveexec_b64 s[24:25], s[24:25]
	v_mov_b32_e32 v13, s7
	v_add_f32_e32 v13, s6, v13
	v_mov_b32_e32 v14, v13
	s_or_b64 exec, exec, s[24:25]
; __device__ __forceinline__ void gla_bcum(const u32x4 a0, const u32x4 a1, const float* wa2, const float* ba, int h, int lane, int wave, float (&bc)[8], float (&bl)[8]) {
;     ...
;     for (int x = 0; x < 4; ++x) { al[2 * x] = __uint_as_float(a0[x] << 16); al[2 * x + 1] = __uint_as_float(a0[x] & 0xffff0000u); al[8 + 2 * x] = __uint_as_float(a1[x] << 16); al[8 + 2 * x + 1] = __uint_as_float(a1[x] & 0xffff0000u); }
; #pragma unroll
;     for (int x = 0; x < 8; ++x) { const int col = h * 64 + 8 * wave + x; float z = ba[col];
; #pragma unroll
;         for (int i = 0; i < 16; ++i) z += al[i] * wa2[i * 256 + col];
;         float la = (fminf(z, 0.f) - __logf(1.f + __expf(-fabsf(z)))) * (1.f / 16.f);
;         la += __builtin_bit_cast(float, __builtin_amdgcn_update_dpp(0, __builtin_bit_cast(int, la), 0x111, 0xf, 0xf, true));
;         la += __builtin_bit_cast(float, __builtin_amdgcn_update_dpp(0, __builtin_bit_cast(int, la), 0x112, 0xf, 0xf, true));
;         la += __builtin_bit_cast(float, __builtin_amdgcn_update_dpp(0, __builtin_bit_cast(int, la), 0x114, 0xf, 0xf, true));
;         la += __builtin_bit_cast(float, __builtin_amdgcn_update_dpp(0, __builtin_bit_cast(int, la), 0x118, 0xf, 0xf, true));
;         const float t0 = __builtin_bit_cast(float, __builtin_amdgcn_readlane(__builtin_bit_cast(int, la), 15)), t1 = __builtin_bit_cast(float, __builtin_amdgcn_readlane(__builtin_bit_cast(int, la), 31)),
;                     t2 = __builtin_bit_cast(float, __builtin_amdgcn_readlane(__builtin_bit_cast(int, la), 47)), t3 = __builtin_bit_cast(float, __builtin_amdgcn_readlane(__builtin_bit_cast(int, la), 63));
;         la += (lane >= 48) ? (t0 + t1) + t2 : (lane >= 32) ? t0 + t1 : (lane >= 16) ? t0 : 0.f;
;         bc[x] = la; bl[x] = ((t0 + t1) + t2) + t3; }
.LBB0_479:
	s_andn2_saveexec_b64 s[22:23], s[22:23]
	v_mov_b32_e32 v13, s7
	v_add_f32_e32 v14, s6, v13
	v_add_f32_e32 v13, s35, v14
	s_or_b64 exec, exec, s[22:23]
	s_mov_b32 s6, 0xbfb8aa3b
	s_waitcnt lgkmcnt(0)
	v_mov_b32_e32 v36, s82
	v_fmac_f32_e32 v36, s83, v59
	v_fmac_f32_e32 v36, s84, v58
	v_fmac_f32_e32 v36, s85, v57
	v_fmac_f32_e32 v36, s86, v56
	v_fmac_f32_e32 v36, s87, v55
	v_fmac_f32_e32 v36, s88, v54
	v_fmac_f32_e32 v36, s89, v53
	v_fmac_f32_e32 v36, s90, v52
	v_fmac_f32_e32 v36, s91, v51
	v_fmac_f32_e32 v36, s94, v50
	v_fmac_f32_e32 v36, s95, v49
	v_fmac_f32_e32 v36, s96, v47
	v_fmac_f32_e32 v36, s97, v46
	v_fmac_f32_e32 v36, s51, v38
	v_fmac_f32_e32 v36, s52, v37
	v_fmac_f32_e32 v36, s53, v15
	s_load_dword s82, s[20:21], 0x8
	s_load_dword s83, s[16:17], 0x8
	s_load_dword s84, s[16:17], 0x408
	s_load_dword s85, s[16:17], 0x808
	s_load_dword s86, s[16:17], 0xc08
	s_load_dword s87, s[16:17], 0x1008
	s_load_dword s88, s[16:17], 0x1408
	s_load_dword s89, s[16:17], 0x1808
	s_load_dword s90, s[16:17], 0x1c08
	s_load_dword s91, s[16:17], 0x2008
	s_load_dword s94, s[16:17], 0x2408
	s_load_dword s95, s[16:17], 0x2808
	s_load_dword s96, s[16:17], 0x2c08
	s_load_dword s97, s[16:17], 0x3008
	s_load_dword s51, s[16:17], 0x3408
	s_load_dword s52, s[16:17], 0x3808
	s_load_dword s53, s[16:17], 0x3c08
	v_mul_f32_e64 v39, |v36|, s6
	v_exp_f32_e32 v39, v39
	s_mov_b32 s6, 0x3f317217
	v_min_f32_e32 v36, 0, v36
	v_add_f32_e32 v39, 1.0, v39
	v_cmp_gt_f32_e32 vcc, s81, v39
	s_nop 1
	v_cndmask_b32_e64 v48, 0, 32, vcc
	v_ldexp_f32 v39, v39, v48
	v_log_f32_e32 v39, v39
	v_cndmask_b32_e32 v48, 0, v231, vcc
	v_mul_f32_e32 v60, 0x3f317217, v39
	v_fma_f32 v60, v39, s6, -v60
	v_fmac_f32_e32 v60, 0x3377d1cf, v39
	s_mov_b32 s6, 0x7f800000
	v_fmac_f32_e32 v60, 0x3f317217, v39
	v_cmp_lt_f32_e64 vcc, |v39|, s6
	s_nop 1
	v_cndmask_b32_e32 v39, v39, v60, vcc
	v_sub_f32_e32 v39, v39, v48
	v_sub_f32_e32 v36, v36, v39
	v_mul_f32_e32 v39, 0x3d800000, v36
	s_nop 1
	v_mov_b32_dpp v39, v39 row_shr:1 row_mask:0xf bank_mask:0xf bound_ctrl:1
	v_fmac_f32_e32 v39, 0x3d800000, v36
	s_nop 1
	v_add_f32_dpp v36, v39, v39 row_shr:2 row_mask:0xf bank_mask:0xf bound_ctrl:1
	s_nop 1
	v_add_f32_dpp v36, v36, v36 row_shr:4 row_mask:0xf bank_mask:0xf bound_ctrl:1
	s_nop 1
	v_add_f32_dpp v36, v36, v36 row_shr:8 row_mask:0xf bank_mask:0xf bound_ctrl:1
	s_nop 0
	v_readlane_b32 s39, v36, 15
	v_readlane_b32 s40, v36, 31
	v_readlane_b32 s37, v36, 47
	v_readlane_b32 s38, v36, 63
	s_and_saveexec_b64 s[6:7], s[8:9]
	s_xor_b64 s[22:23], exec, s[6:7]
	s_cbranch_execz .LBB0_487
	s_and_saveexec_b64 s[6:7], s[10:11]
	s_xor_b64 s[6:7], exec, s[6:7]
	v_mov_b32_e32 v39, s39
	v_mov_b32_e32 v48, s40
	v_cndmask_b32_e64 v39, 0, v39, s[12:13]
	v_add_f32_e32 v48, s39, v48
	s_andn2_saveexec_b64 s[24:25], s[6:7]
	v_mov_b32_e32 v39, s40
	v_add_f32_e32 v39, s39, v39
	v_mov_b32_e32 v48, v39
	s_or_b64 exec, exec, s[24:25]
.LBB0_487:
	s_andn2_saveexec_b64 s[22:23], s[22:23]
	v_mov_b32_e32 v39, s40
	v_add_f32_e32 v48, s39, v39
	v_add_f32_e32 v39, s37, v48
	s_or_b64 exec, exec, s[22:23]
	s_mov_b32 s6, 0xbfb8aa3b
	s_waitcnt lgkmcnt(0)
	v_mov_b32_e32 v60, s82
	v_fmac_f32_e32 v60, s83, v59
	v_fmac_f32_e32 v60, s84, v58
	v_fmac_f32_e32 v60, s85, v57
	v_fmac_f32_e32 v60, s86, v56
	v_fmac_f32_e32 v60, s87, v55
	v_fmac_f32_e32 v60, s88, v54
	v_fmac_f32_e32 v60, s89, v53
	v_fmac_f32_e32 v60, s90, v52
	v_fmac_f32_e32 v60, s91, v51
	v_fmac_f32_e32 v60, s94, v50
	v_fmac_f32_e32 v60, s95, v49
	v_fmac_f32_e32 v60, s96, v47
	v_fmac_f32_e32 v60, s97, v46
	v_fmac_f32_e32 v60, s51, v38
	v_fmac_f32_e32 v60, s52, v37
	v_fmac_f32_e32 v60, s53, v15
	s_load_dword s82, s[20:21], 0xc
	s_load_dword s83, s[16:17], 0xc
	s_load_dword s84, s[16:17], 0x40c
	s_load_dword s85, s[16:17], 0x80c
	s_load_dword s86, s[16:17], 0xc0c
	s_load_dword s87, s[16:17], 0x100c
	s_load_dword s88, s[16:17], 0x140c
	s_load_dword s89, s[16:17], 0x180c
	s_load_dword s90, s[16:17], 0x1c0c
	s_load_dword s91, s[16:17], 0x200c
	s_load_dword s94, s[16:17], 0x240c
	s_load_dword s95, s[16:17], 0x280c
	s_load_dword s96, s[16:17], 0x2c0c
	s_load_dword s97, s[16:17], 0x300c
	s_load_dword s51, s[16:17], 0x340c
	s_load_dword s52, s[16:17], 0x380c
	s_load_dword s53, s[16:17], 0x3c0c
	v_mul_f32_e64 v61, |v60|, s6
	v_exp_f32_e32 v61, v61
	s_mov_b32 s6, 0x3f317217
	v_min_f32_e32 v60, 0, v60
	v_add_f32_e32 v61, 1.0, v61
	v_cmp_gt_f32_e32 vcc, s81, v61
	s_nop 1
	v_cndmask_b32_e64 v62, 0, 32, vcc
	v_ldexp_f32 v61, v61, v62
	v_log_f32_e32 v61, v61
	v_cndmask_b32_e32 v62, 0, v231, vcc
	v_mul_f32_e32 v63, 0x3f317217, v61
	v_fma_f32 v63, v61, s6, -v63
	v_fmac_f32_e32 v63, 0x3377d1cf, v61
	s_mov_b32 s6, 0x7f800000
	v_fmac_f32_e32 v63, 0x3f317217, v61
	v_cmp_lt_f32_e64 vcc, |v61|, s6
	s_nop 1
	v_cndmask_b32_e32 v61, v61, v63, vcc
	v_sub_f32_e32 v61, v61, v62
	v_sub_f32_e32 v60, v60, v61
	v_mul_f32_e32 v61, 0x3d800000, v60
	s_nop 1
	v_mov_b32_dpp v61, v61 row_shr:1 row_mask:0xf bank_mask:0xf bound_ctrl:1
	v_fmac_f32_e32 v61, 0x3d800000, v60
	s_nop 1
	v_add_f32_dpp v60, v61, v61 row_shr:2 row_mask:0xf bank_mask:0xf bound_ctrl:1
	s_nop 1
	v_add_f32_dpp v60, v60, v60 row_shr:4 row_mask:0xf bank_mask:0xf bound_ctrl:1
	s_nop 1
	v_add_f32_dpp v60, v60, v60 row_shr:8 row_mask:0xf bank_mask:0xf bound_ctrl:1
	s_nop 0
	v_readlane_b32 s41, v60, 15
	v_readlane_b32 s42, v60, 31
	v_readlane_b32 s39, v60, 47
	v_readlane_b32 s40, v60, 63
	s_and_saveexec_b64 s[6:7], s[8:9]
	s_xor_b64 s[22:23], exec, s[6:7]
	s_cbranch_execz .LBB0_495
	s_and_saveexec_b64 s[6:7], s[10:11]
	s_xor_b64 s[6:7], exec, s[6:7]
	v_mov_b32_e32 v61, s41
	v_mov_b32_e32 v62, s42
	v_cndmask_b32_e64 v61, 0, v61, s[12:13]
	v_add_f32_e32 v62, s41, v62
	s_andn2_saveexec_b64 s[24:25], s[6:7]
	v_mov_b32_e32 v61, s42
	v_add_f32_e32 v61, s41, v61
	v_mov_b32_e32 v62, v61
	s_or_b64 exec, exec, s[24:25]
; __device__ __forceinline__ void gla_bcum(const u32x4 a0, const u32x4 a1, const float* wa2, const float* ba, int h, int lane, int wave, float (&bc)[8], float (&bl)[8]) {
;     ...
;     for (int x = 0; x < 4; ++x) { al[2 * x] = __uint_as_float(a0[x] << 16); al[2 * x + 1] = __uint_as_float(a0[x] & 0xffff0000u); al[8 + 2 * x] = __uint_as_float(a1[x] << 16); al[8 + 2 * x + 1] = __uint_as_float(a1[x] & 0xffff0000u); }
; #pragma unroll
;     for (int x = 0; x < 8; ++x) { const int col = h * 64 + 8 * wave + x; float z = ba[col];
; #pragma unroll
;         for (int i = 0; i < 16; ++i) z += al[i] * wa2[i * 256 + col];
;         float la = (fminf(z, 0.f) - __logf(1.f + __expf(-fabsf(z)))) * (1.f / 16.f);
;         la += __builtin_bit_cast(float, __builtin_amdgcn_update_dpp(0, __builtin_bit_cast(int, la), 0x111, 0xf, 0xf, true));
;         la += __builtin_bit_cast(float, __builtin_amdgcn_update_dpp(0, __builtin_bit_cast(int, la), 0x112, 0xf, 0xf, true));
;         la += __builtin_bit_cast(float, __builtin_amdgcn_update_dpp(0, __builtin_bit_cast(int, la), 0x114, 0xf, 0xf, true));
;         la += __builtin_bit_cast(float, __builtin_amdgcn_update_dpp(0, __builtin_bit_cast(int, la), 0x118, 0xf, 0xf, true));
;         const float t0 = __builtin_bit_cast(float, __builtin_amdgcn_readlane(__builtin_bit_cast(int, la), 15)), t1 = __builtin_bit_cast(float, __builtin_amdgcn_readlane(__builtin_bit_cast(int, la), 31)),
;                     t2 = __builtin_bit_cast(float, __builtin_amdgcn_readlane(__builtin_bit_cast(int, la), 47)), t3 = __builtin_bit_cast(float, __builtin_amdgcn_readlane(__builtin_bit_cast(int, la), 63));
;         la += (lane >= 48) ? (t0 + t1) + t2 : (lane >= 32) ? t0 + t1 : (lane >= 16) ? t0 : 0.f;
;         bc[x] = la; bl[x] = ((t0 + t1) + t2) + t3; }
.LBB0_495:
	s_andn2_saveexec_b64 s[22:23], s[22:23]
	v_mov_b32_e32 v61, s42
	v_add_f32_e32 v62, s41, v61
	v_add_f32_e32 v61, s39, v62
	s_or_b64 exec, exec, s[22:23]
	s_mov_b32 s6, 0xbfb8aa3b
	s_waitcnt lgkmcnt(0)
	v_mov_b32_e32 v63, s82
	v_fmac_f32_e32 v63, s83, v59
	v_fmac_f32_e32 v63, s84, v58
	v_fmac_f32_e32 v63, s85, v57
	v_fmac_f32_e32 v63, s86, v56
	v_fmac_f32_e32 v63, s87, v55
	v_fmac_f32_e32 v63, s88, v54
	v_fmac_f32_e32 v63, s89, v53
	v_fmac_f32_e32 v63, s90, v52
	v_fmac_f32_e32 v63, s91, v51
	v_fmac_f32_e32 v63, s94, v50
	v_fmac_f32_e32 v63, s95, v49
	v_fmac_f32_e32 v63, s96, v47
	v_fmac_f32_e32 v63, s97, v46
	v_fmac_f32_e32 v63, s51, v38
	v_fmac_f32_e32 v63, s52, v37
	v_fmac_f32_e32 v63, s53, v15
	s_load_dword s82, s[20:21], 0x10
	s_load_dword s83, s[16:17], 0x10
	s_load_dword s84, s[16:17], 0x410
	s_load_dword s85, s[16:17], 0x810
	s_load_dword s86, s[16:17], 0xc10
	s_load_dword s87, s[16:17], 0x1010
	s_load_dword s88, s[16:17], 0x1410
	s_load_dword s89, s[16:17], 0x1810
	s_load_dword s90, s[16:17], 0x1c10
	s_load_dword s91, s[16:17], 0x2010
	s_load_dword s94, s[16:17], 0x2410
	s_load_dword s95, s[16:17], 0x2810
	s_load_dword s96, s[16:17], 0x2c10
	s_load_dword s97, s[16:17], 0x3010
	s_load_dword s51, s[16:17], 0x3410
	s_load_dword s52, s[16:17], 0x3810
	s_load_dword s53, s[16:17], 0x3c10
	v_mul_f32_e64 v64, |v63|, s6
	v_exp_f32_e32 v64, v64
	s_mov_b32 s6, 0x3f317217
	v_min_f32_e32 v63, 0, v63
	v_add_f32_e32 v64, 1.0, v64
	v_cmp_gt_f32_e32 vcc, s81, v64
	s_nop 1
	v_cndmask_b32_e64 v65, 0, 32, vcc
	v_ldexp_f32 v64, v64, v65
	v_log_f32_e32 v64, v64
	v_cndmask_b32_e32 v65, 0, v231, vcc
	v_mul_f32_e32 v66, 0x3f317217, v64
	v_fma_f32 v66, v64, s6, -v66
	v_fmac_f32_e32 v66, 0x3377d1cf, v64
	s_mov_b32 s6, 0x7f800000
	v_fmac_f32_e32 v66, 0x3f317217, v64
	v_cmp_lt_f32_e64 vcc, |v64|, s6
	s_nop 1
	v_cndmask_b32_e32 v64, v64, v66, vcc
	v_sub_f32_e32 v64, v64, v65
	v_sub_f32_e32 v63, v63, v64
	v_mul_f32_e32 v64, 0x3d800000, v63
	s_nop 1
	v_mov_b32_dpp v64, v64 row_shr:1 row_mask:0xf bank_mask:0xf bound_ctrl:1
	v_fmac_f32_e32 v64, 0x3d800000, v63
	s_nop 1
	v_add_f32_dpp v63, v64, v64 row_shr:2 row_mask:0xf bank_mask:0xf bound_ctrl:1
	s_nop 1
	v_add_f32_dpp v63, v63, v63 row_shr:4 row_mask:0xf bank_mask:0xf bound_ctrl:1
	s_nop 1
	v_add_f32_dpp v63, v63, v63 row_shr:8 row_mask:0xf bank_mask:0xf bound_ctrl:1
	s_nop 0
	v_readlane_b32 s43, v63, 15
	v_readlane_b32 s44, v63, 31
	v_readlane_b32 s41, v63, 47
	v_readlane_b32 s42, v63, 63
	s_and_saveexec_b64 s[6:7], s[8:9]
	s_xor_b64 s[22:23], exec, s[6:7]
	s_cbranch_execz .LBB0_503
	s_and_saveexec_b64 s[6:7], s[10:11]
	s_xor_b64 s[6:7], exec, s[6:7]
	v_mov_b32_e32 v64, s43
	v_mov_b32_e32 v65, s44
	v_cndmask_b32_e64 v64, 0, v64, s[12:13]
	v_add_f32_e32 v65, s43, v65
	s_andn2_saveexec_b64 s[24:25], s[6:7]
	v_mov_b32_e32 v64, s44
	v_add_f32_e32 v64, s43, v64
	v_mov_b32_e32 v65, v64
	s_or_b64 exec, exec, s[24:25]
.LBB0_503:
	s_andn2_saveexec_b64 s[22:23], s[22:23]
	v_mov_b32_e32 v64, s44
	v_add_f32_e32 v65, s43, v64
	v_add_f32_e32 v64, s41, v65
	s_or_b64 exec, exec, s[22:23]
	s_mov_b32 s6, 0xbfb8aa3b
	s_waitcnt lgkmcnt(0)
	v_mov_b32_e32 v66, s82
	v_fmac_f32_e32 v66, s83, v59
	v_fmac_f32_e32 v66, s84, v58
	v_fmac_f32_e32 v66, s85, v57
	v_fmac_f32_e32 v66, s86, v56
	v_fmac_f32_e32 v66, s87, v55
	v_fmac_f32_e32 v66, s88, v54
	v_fmac_f32_e32 v66, s89, v53
	v_fmac_f32_e32 v66, s90, v52
	v_fmac_f32_e32 v66, s91, v51
	v_fmac_f32_e32 v66, s94, v50
	v_fmac_f32_e32 v66, s95, v49
	v_fmac_f32_e32 v66, s96, v47
	v_fmac_f32_e32 v66, s97, v46
	v_fmac_f32_e32 v66, s51, v38
	v_fmac_f32_e32 v66, s52, v37
	v_fmac_f32_e32 v66, s53, v15
	s_load_dword s82, s[20:21], 0x14
	s_load_dword s83, s[16:17], 0x14
	s_load_dword s84, s[16:17], 0x414
	s_load_dword s85, s[16:17], 0x814
	s_load_dword s86, s[16:17], 0xc14
	s_load_dword s87, s[16:17], 0x1014
	s_load_dword s88, s[16:17], 0x1414
	s_load_dword s89, s[16:17], 0x1814
	s_load_dword s90, s[16:17], 0x1c14
	s_load_dword s91, s[16:17], 0x2014
	s_load_dword s94, s[16:17], 0x2414
	s_load_dword s95, s[16:17], 0x2814
	s_load_dword s96, s[16:17], 0x2c14
	s_load_dword s97, s[16:17], 0x3014
	s_load_dword s51, s[16:17], 0x3414
	s_load_dword s52, s[16:17], 0x3814
	s_load_dword s53, s[16:17], 0x3c14
	v_mul_f32_e64 v67, |v66|, s6
	v_exp_f32_e32 v67, v67
	s_mov_b32 s6, 0x3f317217
	v_min_f32_e32 v66, 0, v66
	v_add_f32_e32 v67, 1.0, v67
	v_cmp_gt_f32_e32 vcc, s81, v67
	s_nop 1
	v_cndmask_b32_e64 v68, 0, 32, vcc
	v_ldexp_f32 v67, v67, v68
	v_log_f32_e32 v67, v67
	v_cndmask_b32_e32 v68, 0, v231, vcc
	v_mul_f32_e32 v69, 0x3f317217, v67
	v_fma_f32 v69, v67, s6, -v69
	v_fmac_f32_e32 v69, 0x3377d1cf, v67
	s_mov_b32 s6, 0x7f800000
	v_fmac_f32_e32 v69, 0x3f317217, v67
	v_cmp_lt_f32_e64 vcc, |v67|, s6
	s_nop 1
	v_cndmask_b32_e32 v67, v67, v69, vcc
	v_sub_f32_e32 v67, v67, v68
	v_sub_f32_e32 v66, v66, v67
	v_mul_f32_e32 v67, 0x3d800000, v66
	s_nop 1
	v_mov_b32_dpp v67, v67 row_shr:1 row_mask:0xf bank_mask:0xf bound_ctrl:1
	v_fmac_f32_e32 v67, 0x3d800000, v66
	s_nop 1
	v_add_f32_dpp v66, v67, v67 row_shr:2 row_mask:0xf bank_mask:0xf bound_ctrl:1
	s_nop 1
	v_add_f32_dpp v66, v66, v66 row_shr:4 row_mask:0xf bank_mask:0xf bound_ctrl:1
	s_nop 1
	v_add_f32_dpp v66, v66, v66 row_shr:8 row_mask:0xf bank_mask:0xf bound_ctrl:1
	s_nop 0
	v_readlane_b32 s45, v66, 15
	v_readlane_b32 s46, v66, 31
	v_readlane_b32 s43, v66, 47
	v_readlane_b32 s44, v66, 63
	s_and_saveexec_b64 s[6:7], s[8:9]
	s_xor_b64 s[22:23], exec, s[6:7]
	s_cbranch_execz .LBB0_511
	s_and_saveexec_b64 s[6:7], s[10:11]
	s_xor_b64 s[6:7], exec, s[6:7]
	v_mov_b32_e32 v67, s45
	v_mov_b32_e32 v68, s46
	v_cndmask_b32_e64 v67, 0, v67, s[12:13]
	v_add_f32_e32 v68, s45, v68
	s_andn2_saveexec_b64 s[24:25], s[6:7]
	v_mov_b32_e32 v67, s46
	v_add_f32_e32 v67, s45, v67
	v_mov_b32_e32 v68, v67
	s_or_b64 exec, exec, s[24:25]
; __device__ __forceinline__ void gla_bcum(const u32x4 a0, const u32x4 a1, const float* wa2, const float* ba, int h, int lane, int wave, float (&bc)[8], float (&bl)[8]) {
;     ...
;     for (int x = 0; x < 4; ++x) { al[2 * x] = __uint_as_float(a0[x] << 16); al[2 * x + 1] = __uint_as_float(a0[x] & 0xffff0000u); al[8 + 2 * x] = __uint_as_float(a1[x] << 16); al[8 + 2 * x + 1] = __uint_as_float(a1[x] & 0xffff0000u); }
; #pragma unroll
;     for (int x = 0; x < 8; ++x) { const int col = h * 64 + 8 * wave + x; float z = ba[col];
; #pragma unroll
;         for (int i = 0; i < 16; ++i) z += al[i] * wa2[i * 256 + col];
;         float la = (fminf(z, 0.f) - __logf(1.f + __expf(-fabsf(z)))) * (1.f / 16.f);
;         la += __builtin_bit_cast(float, __builtin_amdgcn_update_dpp(0, __builtin_bit_cast(int, la), 0x111, 0xf, 0xf, true));
;         la += __builtin_bit_cast(float, __builtin_amdgcn_update_dpp(0, __builtin_bit_cast(int, la), 0x112, 0xf, 0xf, true));
;         la += __builtin_bit_cast(float, __builtin_amdgcn_update_dpp(0, __builtin_bit_cast(int, la), 0x114, 0xf, 0xf, true));
;         la += __builtin_bit_cast(float, __builtin_amdgcn_update_dpp(0, __builtin_bit_cast(int, la), 0x118, 0xf, 0xf, true));
;         const float t0 = __builtin_bit_cast(float, __builtin_amdgcn_readlane(__builtin_bit_cast(int, la), 15)), t1 = __builtin_bit_cast(float, __builtin_amdgcn_readlane(__builtin_bit_cast(int, la), 31)),
;                     t2 = __builtin_bit_cast(float, __builtin_amdgcn_readlane(__builtin_bit_cast(int, la), 47)), t3 = __builtin_bit_cast(float, __builtin_amdgcn_readlane(__builtin_bit_cast(int, la), 63));
;         la += (lane >= 48) ? (t0 + t1) + t2 : (lane >= 32) ? t0 + t1 : (lane >= 16) ? t0 : 0.f;
;         bc[x] = la; bl[x] = ((t0 + t1) + t2) + t3; }
.LBB0_511:
	s_andn2_saveexec_b64 s[22:23], s[22:23]
	v_mov_b32_e32 v67, s46
	v_add_f32_e32 v68, s45, v67
	v_add_f32_e32 v67, s43, v68
	s_or_b64 exec, exec, s[22:23]
	s_mov_b32 s6, 0xbfb8aa3b
	s_waitcnt lgkmcnt(0)
	v_mov_b32_e32 v69, s82
	v_fmac_f32_e32 v69, s83, v59
	v_fmac_f32_e32 v69, s84, v58
	v_fmac_f32_e32 v69, s85, v57
	v_fmac_f32_e32 v69, s86, v56
	v_fmac_f32_e32 v69, s87, v55
	v_fmac_f32_e32 v69, s88, v54
	v_fmac_f32_e32 v69, s89, v53
	v_fmac_f32_e32 v69, s90, v52
	v_fmac_f32_e32 v69, s91, v51
	v_fmac_f32_e32 v69, s94, v50
	v_fmac_f32_e32 v69, s95, v49
	v_fmac_f32_e32 v69, s96, v47
	v_fmac_f32_e32 v69, s97, v46
	v_fmac_f32_e32 v69, s51, v38
	v_fmac_f32_e32 v69, s52, v37
	v_fmac_f32_e32 v69, s53, v15
	s_load_dword s82, s[20:21], 0x18
	s_load_dword s83, s[16:17], 0x18
	s_load_dword s84, s[16:17], 0x418
	s_load_dword s85, s[16:17], 0x818
	s_load_dword s86, s[16:17], 0xc18
	s_load_dword s87, s[16:17], 0x1018
	s_load_dword s88, s[16:17], 0x1418
	s_load_dword s89, s[16:17], 0x1818
	s_load_dword s90, s[16:17], 0x1c18
	s_load_dword s91, s[16:17], 0x2018
	s_load_dword s94, s[16:17], 0x2418
	s_load_dword s95, s[16:17], 0x2818
	s_load_dword s96, s[16:17], 0x2c18
	s_load_dword s97, s[16:17], 0x3018
	s_load_dword s51, s[16:17], 0x3418
	s_load_dword s52, s[16:17], 0x3818
	s_load_dword s53, s[16:17], 0x3c18
	v_mul_f32_e64 v70, |v69|, s6
	v_exp_f32_e32 v70, v70
	s_mov_b32 s6, 0x3f317217
	v_min_f32_e32 v69, 0, v69
	v_add_f32_e32 v70, 1.0, v70
	v_cmp_gt_f32_e32 vcc, s81, v70
	s_nop 1
	v_cndmask_b32_e64 v71, 0, 32, vcc
	v_ldexp_f32 v70, v70, v71
	v_log_f32_e32 v70, v70
	v_cndmask_b32_e32 v71, 0, v231, vcc
	v_mul_f32_e32 v72, 0x3f317217, v70
	v_fma_f32 v72, v70, s6, -v72
	v_fmac_f32_e32 v72, 0x3377d1cf, v70
	s_mov_b32 s6, 0x7f800000
	v_fmac_f32_e32 v72, 0x3f317217, v70
	v_cmp_lt_f32_e64 vcc, |v70|, s6
	s_nop 1
	v_cndmask_b32_e32 v70, v70, v72, vcc
	v_sub_f32_e32 v70, v70, v71
	v_sub_f32_e32 v69, v69, v70
	v_mul_f32_e32 v70, 0x3d800000, v69
	s_nop 1
	v_mov_b32_dpp v70, v70 row_shr:1 row_mask:0xf bank_mask:0xf bound_ctrl:1
	v_fmac_f32_e32 v70, 0x3d800000, v69
	s_nop 1
	v_add_f32_dpp v69, v70, v70 row_shr:2 row_mask:0xf bank_mask:0xf bound_ctrl:1
	s_nop 1
	v_add_f32_dpp v69, v69, v69 row_shr:4 row_mask:0xf bank_mask:0xf bound_ctrl:1
	s_nop 1
	v_add_f32_dpp v69, v69, v69 row_shr:8 row_mask:0xf bank_mask:0xf bound_ctrl:1
	s_nop 0
	v_readlane_b32 s47, v69, 15
	v_readlane_b32 s48, v69, 31
	v_readlane_b32 s45, v69, 47
	v_readlane_b32 s46, v69, 63
	s_and_saveexec_b64 s[6:7], s[8:9]
	s_xor_b64 s[22:23], exec, s[6:7]
	s_cbranch_execz .LBB0_519
	s_and_saveexec_b64 s[6:7], s[10:11]
	s_xor_b64 s[6:7], exec, s[6:7]
	v_mov_b32_e32 v70, s47
	v_mov_b32_e32 v71, s48
	v_cndmask_b32_e64 v70, 0, v70, s[12:13]
	v_add_f32_e32 v71, s47, v71
	s_andn2_saveexec_b64 s[24:25], s[6:7]
	v_mov_b32_e32 v70, s48
	v_add_f32_e32 v70, s47, v70
	v_mov_b32_e32 v71, v70
	s_or_b64 exec, exec, s[24:25]
; __device__ __forceinline__ void gla_bcum(const u32x4 a0, const u32x4 a1, const float* wa2, const float* ba, int h, int lane, int wave, float (&bc)[8], float (&bl)[8]) {
;     ...
;     for (int x = 0; x < 4; ++x) { al[2 * x] = __uint_as_float(a0[x] << 16); al[2 * x + 1] = __uint_as_float(a0[x] & 0xffff0000u); al[8 + 2 * x] = __uint_as_float(a1[x] << 16); al[8 + 2 * x + 1] = __uint_as_float(a1[x] & 0xffff0000u); }
; #pragma unroll
;     for (int x = 0; x < 8; ++x) { const int col = h * 64 + 8 * wave + x; float z = ba[col];
; #pragma unroll
;         for (int i = 0; i < 16; ++i) z += al[i] * wa2[i * 256 + col];
;         float la = (fminf(z, 0.f) - __logf(1.f + __expf(-fabsf(z)))) * (1.f / 16.f);
;         la += __builtin_bit_cast(float, __builtin_amdgcn_update_dpp(0, __builtin_bit_cast(int, la), 0x111, 0xf, 0xf, true));
;         la += __builtin_bit_cast(float, __builtin_amdgcn_update_dpp(0, __builtin_bit_cast(int, la), 0x112, 0xf, 0xf, true));
;         la += __builtin_bit_cast(float, __builtin_amdgcn_update_dpp(0, __builtin_bit_cast(int, la), 0x114, 0xf, 0xf, true));
;         la += __builtin_bit_cast(float, __builtin_amdgcn_update_dpp(0, __builtin_bit_cast(int, la), 0x118, 0xf, 0xf, true));
;         const float t0 = __builtin_bit_cast(float, __builtin_amdgcn_readlane(__builtin_bit_cast(int, la), 15)), t1 = __builtin_bit_cast(float, __builtin_amdgcn_readlane(__builtin_bit_cast(int, la), 31)),
;                     t2 = __builtin_bit_cast(float, __builtin_amdgcn_readlane(__builtin_bit_cast(int, la), 47)), t3 = __builtin_bit_cast(float, __builtin_amdgcn_readlane(__builtin_bit_cast(int, la), 63));
;         la += (lane >= 48) ? (t0 + t1) + t2 : (lane >= 32) ? t0 + t1 : (lane >= 16) ? t0 : 0.f;
;         bc[x] = la; bl[x] = ((t0 + t1) + t2) + t3; }
.LBB0_519:
	s_andn2_saveexec_b64 s[22:23], s[22:23]
	v_mov_b32_e32 v70, s48
	v_add_f32_e32 v71, s47, v70
	v_add_f32_e32 v70, s45, v71
	s_or_b64 exec, exec, s[22:23]
	s_mov_b32 s6, 0xbfb8aa3b
	s_waitcnt lgkmcnt(0)
	v_mov_b32_e32 v72, s82
	v_fmac_f32_e32 v72, s83, v59
	v_fmac_f32_e32 v72, s84, v58
	v_fmac_f32_e32 v72, s85, v57
	v_fmac_f32_e32 v72, s86, v56
	v_fmac_f32_e32 v72, s87, v55
	v_fmac_f32_e32 v72, s88, v54
	v_fmac_f32_e32 v72, s89, v53
	v_fmac_f32_e32 v72, s90, v52
	v_fmac_f32_e32 v72, s91, v51
	v_fmac_f32_e32 v72, s94, v50
	v_fmac_f32_e32 v72, s95, v49
	v_fmac_f32_e32 v72, s96, v47
	v_fmac_f32_e32 v72, s97, v46
	v_fmac_f32_e32 v72, s51, v38
	v_fmac_f32_e32 v72, s52, v37
	v_fmac_f32_e32 v72, s53, v15
	s_load_dword s82, s[20:21], 0x1c
	s_load_dword s83, s[16:17], 0x1c
	s_load_dword s84, s[16:17], 0x41c
	s_load_dword s85, s[16:17], 0x81c
	s_load_dword s86, s[16:17], 0xc1c
	s_load_dword s87, s[16:17], 0x101c
	s_load_dword s88, s[16:17], 0x141c
	s_load_dword s89, s[16:17], 0x181c
	s_load_dword s90, s[16:17], 0x1c1c
	s_load_dword s91, s[16:17], 0x201c
	s_load_dword s94, s[16:17], 0x241c
	s_load_dword s95, s[16:17], 0x281c
	s_load_dword s96, s[16:17], 0x2c1c
	s_load_dword s97, s[16:17], 0x301c
	s_load_dword s51, s[16:17], 0x341c
	s_load_dword s52, s[16:17], 0x381c
	s_load_dword s53, s[16:17], 0x3c1c
	v_mul_f32_e64 v73, |v72|, s6
	v_exp_f32_e32 v73, v73
	s_mov_b32 s6, 0x3f317217
	v_min_f32_e32 v72, 0, v72
	v_add_f32_e32 v73, 1.0, v73
	v_cmp_gt_f32_e32 vcc, s81, v73
	s_nop 1
	v_cndmask_b32_e64 v74, 0, 32, vcc
	v_ldexp_f32 v73, v73, v74
	v_log_f32_e32 v73, v73
	v_cndmask_b32_e32 v74, 0, v231, vcc
	v_mul_f32_e32 v75, 0x3f317217, v73
	v_fma_f32 v75, v73, s6, -v75
	v_fmac_f32_e32 v75, 0x3377d1cf, v73
	s_mov_b32 s6, 0x7f800000
	v_fmac_f32_e32 v75, 0x3f317217, v73
	v_cmp_lt_f32_e64 vcc, |v73|, s6
	s_nop 1
	v_cndmask_b32_e32 v73, v73, v75, vcc
	v_sub_f32_e32 v73, v73, v74
	v_sub_f32_e32 v72, v72, v73
	v_mul_f32_e32 v73, 0x3d800000, v72
	s_nop 1
	v_mov_b32_dpp v73, v73 row_shr:1 row_mask:0xf bank_mask:0xf bound_ctrl:1
	v_fmac_f32_e32 v73, 0x3d800000, v72
	s_nop 1
	v_add_f32_dpp v72, v73, v73 row_shr:2 row_mask:0xf bank_mask:0xf bound_ctrl:1
	s_nop 1
	v_add_f32_dpp v72, v72, v72 row_shr:4 row_mask:0xf bank_mask:0xf bound_ctrl:1
	s_nop 1
	v_add_f32_dpp v72, v72, v72 row_shr:8 row_mask:0xf bank_mask:0xf bound_ctrl:1
	s_nop 0
	v_readlane_b32 s49, v72, 15
	v_readlane_b32 s58, v72, 31
	v_readlane_b32 s47, v72, 47
	v_readlane_b32 s48, v72, 63
	s_and_saveexec_b64 s[6:7], s[8:9]
	s_xor_b64 s[22:23], exec, s[6:7]
	s_cbranch_execz .LBB0_527
	s_and_saveexec_b64 s[6:7], s[10:11]
	s_xor_b64 s[6:7], exec, s[6:7]
	v_mov_b32_e32 v73, s49
	v_mov_b32_e32 v74, s58
	v_cndmask_b32_e64 v73, 0, v73, s[12:13]
	v_add_f32_e32 v74, s49, v74
	s_andn2_saveexec_b64 s[24:25], s[6:7]
	v_mov_b32_e32 v73, s58
	v_add_f32_e32 v73, s49, v73
	v_mov_b32_e32 v74, v73
	s_or_b64 exec, exec, s[24:25]
.LBB0_527:
	s_andn2_saveexec_b64 s[22:23], s[22:23]
	v_mov_b32_e32 v73, s58
	v_add_f32_e32 v74, s49, v73
	v_add_f32_e32 v73, s47, v74
	s_or_b64 exec, exec, s[22:23]
	s_mov_b32 s6, 0xbfb8aa3b
	s_waitcnt lgkmcnt(0)
	v_mov_b32_e32 v75, s82
	v_fmac_f32_e32 v75, s83, v59
	v_fmac_f32_e32 v75, s84, v58
	v_fmac_f32_e32 v75, s85, v57
	v_fmac_f32_e32 v75, s86, v56
	v_fmac_f32_e32 v75, s87, v55
	v_fmac_f32_e32 v75, s88, v54
	v_fmac_f32_e32 v75, s89, v53
	v_fmac_f32_e32 v75, s90, v52
	v_fmac_f32_e32 v75, s91, v51
	v_fmac_f32_e32 v75, s94, v50
	v_fmac_f32_e32 v75, s95, v49
	v_fmac_f32_e32 v75, s96, v47
	v_fmac_f32_e32 v75, s97, v46
	v_fmac_f32_e32 v75, s51, v38
	v_fmac_f32_e32 v75, s52, v37
	v_fmac_f32_e32 v75, s53, v15
	v_readlane_b32 s82, v255, 29
	v_readlane_b32 s83, v255, 30
	v_readlane_b32 s84, v255, 31
	v_readlane_b32 s85, v255, 32
	v_readlane_b32 s86, v255, 33
	v_readlane_b32 s87, v255, 34
	v_readlane_b32 s88, v255, 35
	v_readlane_b32 s89, v255, 36
	v_readlane_b32 s90, v255, 37
	v_readlane_b32 s91, v255, 38
	v_readlane_b32 s94, v255, 39
	v_readlane_b32 s95, v255, 40
	v_readlane_b32 s96, v255, 41
	v_readlane_b32 s97, v255, 42
	v_readlane_b32 s51, v255, 43
	v_readlane_b32 s52, v255, 44
	v_readlane_b32 s53, v255, 45
	s_waitcnt vmcnt(0)
	v_mul_f32_e64 v37, |v75|, s6
	v_exp_f32_e32 v37, v37
	s_mov_b32 s6, 0x3f317217
	v_min_f32_e32 v15, 0, v75
	v_add_f32_e32 v37, 1.0, v37
	v_cmp_gt_f32_e32 vcc, s81, v37
	s_nop 1
	v_cndmask_b32_e64 v38, 0, 32, vcc
	v_ldexp_f32 v37, v37, v38
	v_log_f32_e32 v37, v37
	s_nop 0
	v_mul_f32_e32 v38, 0x3f317217, v37
	v_fma_f32 v38, v37, s6, -v38
	v_fmac_f32_e32 v38, 0x3377d1cf, v37
	s_mov_b32 s6, 0x7f800000
	v_fmac_f32_e32 v38, 0x3f317217, v37
	v_cmp_lt_f32_e64 s[16:17], |v37|, s6
	s_nop 1
	v_cndmask_b32_e64 v37, v37, v38, s[16:17]
	v_cndmask_b32_e32 v38, 0, v231, vcc
	v_sub_f32_e32 v37, v37, v38
	v_sub_f32_e32 v15, v15, v37
	v_mul_f32_e32 v37, 0x3d800000, v15
	s_nop 1
	v_mov_b32_dpp v37, v37 row_shr:1 row_mask:0xf bank_mask:0xf bound_ctrl:1
	v_fmac_f32_e32 v37, 0x3d800000, v15
	s_nop 1
	v_add_f32_dpp v15, v37, v37 row_shr:2 row_mask:0xf bank_mask:0xf bound_ctrl:1
	s_nop 1
	v_add_f32_dpp v15, v15, v15 row_shr:4 row_mask:0xf bank_mask:0xf bound_ctrl:1
	s_nop 1
	v_add_f32_dpp v49, v15, v15 row_shr:8 row_mask:0xf bank_mask:0xf bound_ctrl:1
	s_nop 0
	v_readlane_b32 s24, v49, 15
	v_readlane_b32 s25, v49, 31
	v_readlane_b32 s22, v49, 47
	v_readlane_b32 s23, v49, 63
	s_and_saveexec_b64 s[6:7], s[8:9]
	s_xor_b64 s[16:17], exec, s[6:7]
	s_cbranch_execz .LBB0_535
	s_and_saveexec_b64 s[6:7], s[10:11]
	s_xor_b64 s[6:7], exec, s[6:7]
	v_mov_b32_e32 v15, s24
	v_cndmask_b32_e64 v50, 0, v15, s[12:13]
	v_mov_b32_e32 v15, s25
	v_add_f32_e32 v51, s24, v15
	s_andn2_saveexec_b64 s[20:21], s[6:7]
	v_mov_b32_e32 v15, s25
	v_add_f32_e32 v50, s24, v15
	v_mov_b32_e32 v51, v50
	s_or_b64 exec, exec, s[20:21]
